# compress: activation tile built once per workgroup in LDS, K loop reads A fragments from LDS
# speedup vs baseline: 1.0049x; 1.0049x over previous
; __device__ __forceinline__ int mk_ltid() { int t = threadIdx.x; asm volatile("" : "+v"(t)); return t; }
; #define LAS __attribute__((address_space(3)))
; __device__ __forceinline__ v16f mfma32(v8s a, v8s b, v16f c) { return __builtin_amdgcn_mfma_f32_32x32x16_bf16(a, b, c, 0, 0, 0); }
; __device__ __forceinline__ void compress_unit(LAS unsigned char* lds, int u, const bf16_t* QKV, const float* pe_k, const float* pe_v,
;                                               const bf16_t* CW1  , const bf16_t* CW2  , bf16_t* KCMP, bf16_t* VCMP) {
;     const int tid = mk_ltid(), lane = tid & 63, w = __builtin_amdgcn_readfirstlane(tid >> 6), r32 = lane & 31, hi = lane >> 5;
;     const int kv = u >> 6, b = (u >> 4) & 3, g = (u >> 3) & 1, ch = u & 7;
;     const float* pe = kv ? pe_v : pe_k;
;     const bf16_t* W1 = CW1 + (size_t)kv * 256 * 2048; const bf16_t* W2 = CW2 + (size_t)kv * 64 * 256;
;     bf16_t* OUT = (kv ? VCMP : KCMP) + (size_t)((b * 2 + g) * 256 + ch * 32) * 64;
;     const int n = ch * 32 + r32;
;     const bf16_t* Ag = QKV + (size_t)(b * SEQ + 16 * n) * EVEN_PAD + (kv ? E_VC : E_KC) + g * 64 + hi * 8;
;     const bf16_t* Bg = W1 + (size_t)(32 * w + r32) * 2048 + hi * 8;
;     LAS bf16_t* HID = (LAS bf16_t*)lds;
;     LAS float* PE = (LAS float*)(lds + 20480);
;     v16f acc;
; #pragma unroll
;     for (int r = 0; r < 16; ++r) acc[r] = 0.f;
;     __syncthreads();
;     *(LAS v4f*)(PE + tid * 4) = *(const v4f*)(pe + tid * 4);
;     __syncthreads();
; #pragma unroll 8
;     for (int st = 0; st < 128; ++st) {
;         const int li = st >> 2, d0 = (st & 3) * 16;
;         const v4u ar = *(const v4u*)(Ag + (size_t)li * EVEN_PAD + d0);
;         const v4f pa = *(const LAS v4f*)(PE + li * 64 + d0 + hi * 8), pb = *(const LAS v4f*)(PE + li * 64 + d0 + hi * 8 + 4);
;         const v8s bfr = *(const v8s*)(Bg + st * 16);
;         v4u aw;
;         aw.x = pkbf(__uint_as_float(ar.x << 16) + pa.x, __uint_as_float(ar.x & 0xffff0000u) + pa.y);
;         aw.y = pkbf(__uint_as_float(ar.y << 16) + pa.z, __uint_as_float(ar.y & 0xffff0000u) + pa.w);
;         aw.z = pkbf(__uint_as_float(ar.z << 16) + pb.x, __uint_as_float(ar.z & 0xffff0000u) + pb.y);
;         aw.w = pkbf(__uint_as_float(ar.w << 16) + pb.z, __uint_as_float(ar.w & 0xffff0000u) + pb.w);
;         acc = mfma32(__builtin_bit_cast(v8s, aw), bfr, acc);
.LBB0_411:
	v_mov_b32_e32 v0, v202
	s_ashr_i32 s12, s18, 6
	v_readfirstlane_b32 s10, v0
	s_ashr_i32 s29, s10, 6
	s_bfe_u32 s11, s18, 0x20004
	s_ashr_i32 s13, s12, 31
	s_lshl_b32 s10, s18, 5
	s_lshr_b32 s28, s18, 3
	s_lshl_b64 s[16:17], s[12:13], 20
	s_and_b32 s27, s10, 0xe0
	s_lshl_b32 s30, s11, 12
	s_lshl_b32 s10, s29, 5
	v_and_b32_e32 v41, 31, v0
	s_cmp_lt_u32 s18, 64
	s_cselect_b64 s[14:15], -1, 0
	v_or_b32_e32 v2, s27, v41
	v_lshl_or_b32 v2, v2, 4, s30
	s_and_b64 s[30:31], s[14:15], exec
	s_cselect_b32 s30, s4, s6
	s_movk_i32 s34, 0x1400
	v_mul_u32_u24_e32 v6, 0xe00, v2
	s_cselect_b32 s31, s5, s7
	s_cselect_b32 s34, s34, 0x1500
	s_add_u32 s30, s30, s8
	v_lshlrev_b32_e32 v2, 2, v0
	s_addc_u32 s31, s31, s9
	v_ashrrev_i32_e32 v3, 31, v2
	v_lshl_add_u64 v[2:3], v[2:3], 2, s[30:31]
	s_barrier
	global_load_dwordx4 v[2:5], v[2:3], off
	v_bfe_u32 v40, v0, 5, 1
	v_readlane_b32 s30, v254, 61
	v_lshl_add_u32 v0, v0, 4, 0
	v_or_b32_e32 v34, s10, v41
	v_lshl_add_u32 v42, v40, 5, s30
	s_lshl_b32 s30, s18, 4
	s_and_b32 s30, s30, 0x80
	s_or_b32 s30, s30, s34
	s_add_u32 s30, s0, s30
	s_addc_u32 s31, s1, 0
	v_ashrrev_i32_e32 v35, 31, v34
	s_add_u32 s16, s25, s16
	s_addc_u32 s17, s26, s17
	s_waitcnt vmcnt(0)
	ds_write_b128 v0, v[2:5] offset:20480
	v_lshlrev_b32_e32 v2, 1, v6
	v_mov_b32_e32 v3, v1
	v_lshl_add_u64 v[36:37], s[30:31], 0, v[2:3]
	v_lshlrev_b64 v[2:3], 12, v[34:35]
	v_lshl_add_u64 v[38:39], s[16:17], 0, v[2:3]
	v_mov_b32_e32 v2, 0
	v_lshlrev_b32_e32 v0, 4, v40
	s_mov_b32 s16, 0
	v_mov_b32_e32 v3, v2
	v_mov_b32_e32 v4, v2
	v_mov_b32_e32 v5, v2
	v_mov_b32_e32 v6, v2
	v_mov_b32_e32 v7, v2
	v_mov_b32_e32 v8, v2
	v_mov_b32_e32 v9, v2
	v_mov_b32_e32 v10, v2
	v_mov_b32_e32 v11, v2
	v_mov_b32_e32 v12, v2
	v_mov_b32_e32 v13, v2
	v_mov_b32_e32 v14, v2
	v_mov_b32_e32 v15, v2
	v_mov_b32_e32 v16, v2
	v_mov_b32_e32 v17, v2
	s_waitcnt lgkmcnt(0)
	s_barrier
	v_and_b32_e32 v64, 63, v202
	v_and_b32_e32 v65, 7, v64
	v_lshrrev_b32_e32 v64, 3, v64
	s_lshr_b32 s17, s10, 5
	s_lshl_b32 s34, s17, 6
	v_add_u32_e32 v66, s34, v64
	v_mul_u32_u24_e32 v66, 0x1c00, v66
	v_lshl_add_u32 v66, v65, 4, v66
	s_mul_i32 s34, s17, 0x4040
	s_add_i32 s34, s34, 28672
	v_lshlrev_b32_e32 v67, 7, v64
	v_lshl_add_u32 v67, v65, 4, v67
	v_add_u32_e32 v67, s34, v67
	v_lshlrev_b32_e32 v68, 8, v64
	v_lshl_add_u32 v68, v65, 5, v68
	v_add_u32_e32 v68, 0x5000, v68
	s_bfe_u32 s35, s18, 0x20004
	s_lshl_b32 s35, s35, 12
	s_and_b32 s36, s18, 7
	s_lshl_b32 s36, s36, 9
	s_add_i32 s35, s35, s36
	s_mul_i32 s35, s35, 0x1c00
	s_add_u32 s44, s30, s35
	s_addc_u32 s45, s31, 0
	s_add_u32 s44, s44, 0x1c800000
	s_addc_u32 s45, s45, 0
	global_load_dwordx4 v[104:107], v66, s[44:45]
	s_add_u32 s46, s44, 0xe000
	s_addc_u32 s47, s45, 0
	global_load_dwordx4 v[108:111], v66, s[46:47]
	s_add_u32 s46, s44, 0x1c000
	s_addc_u32 s47, s45, 0
	global_load_dwordx4 v[112:115], v66, s[46:47]
	s_add_u32 s46, s44, 0x2a000
	s_addc_u32 s47, s45, 0
	global_load_dwordx4 v[116:119], v66, s[46:47]
	s_add_u32 s46, s44, 0x1c000
	s_addc_u32 s47, s45, 0
	global_load_dwordx4 v[120:123], v66, s[46:47]
	s_add_u32 s46, s44, 0x2a000
	s_addc_u32 s47, s45, 0
	global_load_dwordx4 v[124:127], v66, s[46:47]
	s_add_u32 s46, s44, 0x38000
	s_addc_u32 s47, s45, 0
	global_load_dwordx4 v[128:131], v66, s[46:47]
	s_add_u32 s46, s44, 0x46000
	s_addc_u32 s47, s45, 0
	global_load_dwordx4 v[132:135], v66, s[46:47]
	s_add_u32 s46, s44, 0x38000
	s_addc_u32 s47, s45, 0
	global_load_dwordx4 v[136:139], v66, s[46:47]
	s_add_u32 s46, s44, 0x46000
	s_addc_u32 s47, s45, 0
	global_load_dwordx4 v[140:143], v66, s[46:47]
	s_add_u32 s46, s44, 0x54000
	s_addc_u32 s47, s45, 0
	global_load_dwordx4 v[144:147], v66, s[46:47]
	s_add_u32 s46, s44, 0x62000
	s_addc_u32 s47, s45, 0
	global_load_dwordx4 v[148:151], v66, s[46:47]
	s_add_u32 s46, s44, 0x54000
	s_addc_u32 s47, s45, 0
	global_load_dwordx4 v[152:155], v66, s[46:47]
	s_add_u32 s46, s44, 0x62000
	s_addc_u32 s47, s45, 0
	global_load_dwordx4 v[156:159], v66, s[46:47]
	s_add_u32 s46, s44, 0x70000
	s_addc_u32 s47, s45, 0
	global_load_dwordx4 v[160:163], v66, s[46:47]
	s_add_u32 s46, s44, 0x7e000
	s_addc_u32 s47, s45, 0
	global_load_dwordx4 v[164:167], v66, s[46:47]
	ds_read_b128 v[72:75], v68
	ds_read_b128 v[76:79], v68 offset:16
	ds_read_b128 v[80:83], v68 offset:2048
	ds_read_b128 v[84:87], v68 offset:2064
	ds_read_b128 v[88:91], v68 offset:4096
	ds_read_b128 v[92:95], v68 offset:4112
	ds_read_b128 v[96:99], v68 offset:6144
	ds_read_b128 v[100:103], v68 offset:6160
	s_waitcnt lgkmcnt(0)
	s_waitcnt vmcnt(15)
	v_lshlrev_b32_e32 v168, 16, v104
	v_and_b32_e32 v169, 0xffff0000, v104
	v_lshlrev_b32_e32 v170, 16, v105
	v_and_b32_e32 v171, 0xffff0000, v105
	v_pk_add_f32 v[168:169], v[72:73], v[168:169]
	v_pk_add_f32 v[170:171], v[74:75], v[170:171]
	v_cvt_pk_bf16_f32 v104, v168, v169
	v_cvt_pk_bf16_f32 v105, v170, v171
	v_lshlrev_b32_e32 v168, 16, v106
	v_and_b32_e32 v169, 0xffff0000, v106
	v_lshlrev_b32_e32 v170, 16, v107
	v_and_b32_e32 v171, 0xffff0000, v107
	v_pk_add_f32 v[168:169], v[76:77], v[168:169]
	v_pk_add_f32 v[170:171], v[78:79], v[170:171]
	v_cvt_pk_bf16_f32 v106, v168, v169
	v_cvt_pk_bf16_f32 v107, v170, v171
	ds_write_b128 v67, v[104:107]
	s_waitcnt vmcnt(14)
	v_lshlrev_b32_e32 v168, 16, v108
	v_and_b32_e32 v169, 0xffff0000, v108
	v_lshlrev_b32_e32 v170, 16, v109
	v_and_b32_e32 v171, 0xffff0000, v109
	v_pk_add_f32 v[168:169], v[80:81], v[168:169]
	v_pk_add_f32 v[170:171], v[82:83], v[170:171]
	v_cvt_pk_bf16_f32 v108, v168, v169
	v_cvt_pk_bf16_f32 v109, v170, v171
	v_lshlrev_b32_e32 v168, 16, v110
	v_and_b32_e32 v169, 0xffff0000, v110
	v_lshlrev_b32_e32 v170, 16, v111
	v_and_b32_e32 v171, 0xffff0000, v111
	v_pk_add_f32 v[168:169], v[84:85], v[168:169]
	v_pk_add_f32 v[170:171], v[86:87], v[170:171]
	v_cvt_pk_bf16_f32 v110, v168, v169
	v_cvt_pk_bf16_f32 v111, v170, v171
	ds_write_b128 v67, v[108:111] offset:1024
	s_waitcnt vmcnt(13)
; #define LAS __attribute__((address_space(3)))
; __device__ __forceinline__ void compress_unit(LAS unsigned char* lds, int u, const bf16_t* QKV, const float* pe_k, const float* pe_v,
;                                               const bf16_t* CW1  , const bf16_t* CW2  , bf16_t* KCMP, bf16_t* VCMP) {
;     ...
;         const v4u ar = *(const v4u*)(Ag + (size_t)li * EVEN_PAD + d0);
;         const v4f pa = *(const LAS v4f*)(PE + li * 64 + d0 + hi * 8), pb = *(const LAS v4f*)(PE + li * 64 + d0 + hi * 8 + 4);
;         const v8s bfr = *(const v8s*)(Bg + st * 16);
;         v4u aw;
;         aw.x = pkbf(__uint_as_float(ar.x << 16) + pa.x, __uint_as_float(ar.x & 0xffff0000u) + pa.y);
;         aw.y = pkbf(__uint_as_float(ar.y << 16) + pa.z, __uint_as_float(ar.y & 0xffff0000u) + pa.w);
;         aw.z = pkbf(__uint_as_float(ar.z << 16) + pb.x, __uint_as_float(ar.z & 0xffff0000u) + pb.y);
;         aw.w = pkbf(__uint_as_float(ar.w << 16) + pb.z, __uint_as_float(ar.w & 0xffff0000u) + pb.w);
	v_lshlrev_b32_e32 v168, 16, v112
	v_and_b32_e32 v169, 0xffff0000, v112
	v_lshlrev_b32_e32 v170, 16, v113
	v_and_b32_e32 v171, 0xffff0000, v113
	v_pk_add_f32 v[168:169], v[88:89], v[168:169]
	v_pk_add_f32 v[170:171], v[90:91], v[170:171]
	v_cvt_pk_bf16_f32 v112, v168, v169
	v_cvt_pk_bf16_f32 v113, v170, v171
	v_lshlrev_b32_e32 v168, 16, v114
	v_and_b32_e32 v169, 0xffff0000, v114
	v_lshlrev_b32_e32 v170, 16, v115
	v_and_b32_e32 v171, 0xffff0000, v115
	v_pk_add_f32 v[168:169], v[92:93], v[168:169]
	v_pk_add_f32 v[170:171], v[94:95], v[170:171]
	v_cvt_pk_bf16_f32 v114, v168, v169
	v_cvt_pk_bf16_f32 v115, v170, v171
	ds_write_b128 v67, v[112:115] offset:2048
	s_waitcnt vmcnt(12)
	v_lshlrev_b32_e32 v168, 16, v116
	v_and_b32_e32 v169, 0xffff0000, v116
	v_lshlrev_b32_e32 v170, 16, v117
	v_and_b32_e32 v171, 0xffff0000, v117
	v_pk_add_f32 v[168:169], v[96:97], v[168:169]
	v_pk_add_f32 v[170:171], v[98:99], v[170:171]
	v_cvt_pk_bf16_f32 v116, v168, v169
	v_cvt_pk_bf16_f32 v117, v170, v171
	v_lshlrev_b32_e32 v168, 16, v118
	v_and_b32_e32 v169, 0xffff0000, v118
	v_lshlrev_b32_e32 v170, 16, v119
	v_and_b32_e32 v171, 0xffff0000, v119
	v_pk_add_f32 v[168:169], v[100:101], v[168:169]
	v_pk_add_f32 v[170:171], v[102:103], v[170:171]
	v_cvt_pk_bf16_f32 v118, v168, v169
	v_cvt_pk_bf16_f32 v119, v170, v171
	ds_write_b128 v67, v[116:119] offset:3072
	s_waitcnt vmcnt(11)
	v_lshlrev_b32_e32 v168, 16, v120
	v_and_b32_e32 v169, 0xffff0000, v120
	v_lshlrev_b32_e32 v170, 16, v121
	v_and_b32_e32 v171, 0xffff0000, v121
	v_pk_add_f32 v[168:169], v[72:73], v[168:169]
	v_pk_add_f32 v[170:171], v[74:75], v[170:171]
	v_cvt_pk_bf16_f32 v120, v168, v169
	v_cvt_pk_bf16_f32 v121, v170, v171
	v_lshlrev_b32_e32 v168, 16, v122
	v_and_b32_e32 v169, 0xffff0000, v122
	v_lshlrev_b32_e32 v170, 16, v123
	v_and_b32_e32 v171, 0xffff0000, v123
	v_pk_add_f32 v[168:169], v[76:77], v[168:169]
	v_pk_add_f32 v[170:171], v[78:79], v[170:171]
	v_cvt_pk_bf16_f32 v122, v168, v169
	v_cvt_pk_bf16_f32 v123, v170, v171
	ds_write_b128 v67, v[120:123] offset:4112
	s_waitcnt vmcnt(10)
	v_lshlrev_b32_e32 v168, 16, v124
	v_and_b32_e32 v169, 0xffff0000, v124
	v_lshlrev_b32_e32 v170, 16, v125
	v_and_b32_e32 v171, 0xffff0000, v125
	v_pk_add_f32 v[168:169], v[80:81], v[168:169]
	v_pk_add_f32 v[170:171], v[82:83], v[170:171]
	v_cvt_pk_bf16_f32 v124, v168, v169
	v_cvt_pk_bf16_f32 v125, v170, v171
	v_lshlrev_b32_e32 v168, 16, v126
	v_and_b32_e32 v169, 0xffff0000, v126
	v_lshlrev_b32_e32 v170, 16, v127
	v_and_b32_e32 v171, 0xffff0000, v127
	v_pk_add_f32 v[168:169], v[84:85], v[168:169]
	v_pk_add_f32 v[170:171], v[86:87], v[170:171]
	v_cvt_pk_bf16_f32 v126, v168, v169
	v_cvt_pk_bf16_f32 v127, v170, v171
	ds_write_b128 v67, v[124:127] offset:5136
	s_waitcnt vmcnt(9)
	v_lshlrev_b32_e32 v168, 16, v128
	v_and_b32_e32 v169, 0xffff0000, v128
	v_lshlrev_b32_e32 v170, 16, v129
	v_and_b32_e32 v171, 0xffff0000, v129
	v_pk_add_f32 v[168:169], v[88:89], v[168:169]
	v_pk_add_f32 v[170:171], v[90:91], v[170:171]
	v_cvt_pk_bf16_f32 v128, v168, v169
	v_cvt_pk_bf16_f32 v129, v170, v171
	v_lshlrev_b32_e32 v168, 16, v130
	v_and_b32_e32 v169, 0xffff0000, v130
	v_lshlrev_b32_e32 v170, 16, v131
	v_and_b32_e32 v171, 0xffff0000, v131
	v_pk_add_f32 v[168:169], v[92:93], v[168:169]
	v_pk_add_f32 v[170:171], v[94:95], v[170:171]
	v_cvt_pk_bf16_f32 v130, v168, v169
	v_cvt_pk_bf16_f32 v131, v170, v171
	ds_write_b128 v67, v[128:131] offset:6160
	s_waitcnt vmcnt(8)
	v_lshlrev_b32_e32 v168, 16, v132
	v_and_b32_e32 v169, 0xffff0000, v132
	v_lshlrev_b32_e32 v170, 16, v133
	v_and_b32_e32 v171, 0xffff0000, v133
	v_pk_add_f32 v[168:169], v[96:97], v[168:169]
	v_pk_add_f32 v[170:171], v[98:99], v[170:171]
	v_cvt_pk_bf16_f32 v132, v168, v169
	v_cvt_pk_bf16_f32 v133, v170, v171
	v_lshlrev_b32_e32 v168, 16, v134
	v_and_b32_e32 v169, 0xffff0000, v134
	v_lshlrev_b32_e32 v170, 16, v135
	v_and_b32_e32 v171, 0xffff0000, v135
	v_pk_add_f32 v[168:169], v[100:101], v[168:169]
	v_pk_add_f32 v[170:171], v[102:103], v[170:171]
	v_cvt_pk_bf16_f32 v134, v168, v169
	v_cvt_pk_bf16_f32 v135, v170, v171
	ds_write_b128 v67, v[132:135] offset:7184
	s_waitcnt vmcnt(7)
	v_lshlrev_b32_e32 v168, 16, v136
	v_and_b32_e32 v169, 0xffff0000, v136
	v_lshlrev_b32_e32 v170, 16, v137
	v_and_b32_e32 v171, 0xffff0000, v137
	v_pk_add_f32 v[168:169], v[72:73], v[168:169]
	v_pk_add_f32 v[170:171], v[74:75], v[170:171]
	v_cvt_pk_bf16_f32 v136, v168, v169
	v_cvt_pk_bf16_f32 v137, v170, v171
	v_lshlrev_b32_e32 v168, 16, v138
	v_and_b32_e32 v169, 0xffff0000, v138
	v_lshlrev_b32_e32 v170, 16, v139
	v_and_b32_e32 v171, 0xffff0000, v139
	v_pk_add_f32 v[168:169], v[76:77], v[168:169]
	v_pk_add_f32 v[170:171], v[78:79], v[170:171]
	v_cvt_pk_bf16_f32 v138, v168, v169
	v_cvt_pk_bf16_f32 v139, v170, v171
	ds_write_b128 v67, v[136:139] offset:8224
	s_waitcnt vmcnt(6)
	v_lshlrev_b32_e32 v168, 16, v140
	v_and_b32_e32 v169, 0xffff0000, v140
	v_lshlrev_b32_e32 v170, 16, v141
	v_and_b32_e32 v171, 0xffff0000, v141
	v_pk_add_f32 v[168:169], v[80:81], v[168:169]
	v_pk_add_f32 v[170:171], v[82:83], v[170:171]
	v_cvt_pk_bf16_f32 v140, v168, v169
	v_cvt_pk_bf16_f32 v141, v170, v171
	v_lshlrev_b32_e32 v168, 16, v142
	v_and_b32_e32 v169, 0xffff0000, v142
	v_lshlrev_b32_e32 v170, 16, v143
	v_and_b32_e32 v171, 0xffff0000, v143
	v_pk_add_f32 v[168:169], v[84:85], v[168:169]
	v_pk_add_f32 v[170:171], v[86:87], v[170:171]
	v_cvt_pk_bf16_f32 v142, v168, v169
	v_cvt_pk_bf16_f32 v143, v170, v171
	ds_write_b128 v67, v[140:143] offset:9248
	s_waitcnt vmcnt(5)
; #define LAS __attribute__((address_space(3)))
; __device__ __forceinline__ v16f mfma32(v8s a, v8s b, v16f c) { return __builtin_amdgcn_mfma_f32_32x32x16_bf16(a, b, c, 0, 0, 0); }
; __device__ __forceinline__ void compress_unit(LAS unsigned char* lds, int u, const bf16_t* QKV, const float* pe_k, const float* pe_v,
;                                               const bf16_t* CW1  , const bf16_t* CW2  , bf16_t* KCMP, bf16_t* VCMP) {
;     ...
;     for (int st = 0; st < 128; ++st) {
;         const int li = st >> 2, d0 = (st & 3) * 16;
;         const v4u ar = *(const v4u*)(Ag + (size_t)li * EVEN_PAD + d0);
;         const v4f pa = *(const LAS v4f*)(PE + li * 64 + d0 + hi * 8), pb = *(const LAS v4f*)(PE + li * 64 + d0 + hi * 8 + 4);
;         const v8s bfr = *(const v8s*)(Bg + st * 16);
;         v4u aw;
;         aw.x = pkbf(__uint_as_float(ar.x << 16) + pa.x, __uint_as_float(ar.x & 0xffff0000u) + pa.y);
;         aw.y = pkbf(__uint_as_float(ar.y << 16) + pa.z, __uint_as_float(ar.y & 0xffff0000u) + pa.w);
;         aw.z = pkbf(__uint_as_float(ar.z << 16) + pb.x, __uint_as_float(ar.z & 0xffff0000u) + pb.y);
;         aw.w = pkbf(__uint_as_float(ar.w << 16) + pb.z, __uint_as_float(ar.w & 0xffff0000u) + pb.w);
;         acc = mfma32(__builtin_bit_cast(v8s, aw), bfr, acc);
	v_lshlrev_b32_e32 v168, 16, v144
	v_and_b32_e32 v169, 0xffff0000, v144
	v_lshlrev_b32_e32 v170, 16, v145
	v_and_b32_e32 v171, 0xffff0000, v145
	v_pk_add_f32 v[168:169], v[88:89], v[168:169]
	v_pk_add_f32 v[170:171], v[90:91], v[170:171]
	v_cvt_pk_bf16_f32 v144, v168, v169
	v_cvt_pk_bf16_f32 v145, v170, v171
	v_lshlrev_b32_e32 v168, 16, v146
	v_and_b32_e32 v169, 0xffff0000, v146
	v_lshlrev_b32_e32 v170, 16, v147
	v_and_b32_e32 v171, 0xffff0000, v147
	v_pk_add_f32 v[168:169], v[92:93], v[168:169]
	v_pk_add_f32 v[170:171], v[94:95], v[170:171]
	v_cvt_pk_bf16_f32 v146, v168, v169
	v_cvt_pk_bf16_f32 v147, v170, v171
	ds_write_b128 v67, v[144:147] offset:10272
	s_waitcnt vmcnt(4)
	v_lshlrev_b32_e32 v168, 16, v148
	v_and_b32_e32 v169, 0xffff0000, v148
	v_lshlrev_b32_e32 v170, 16, v149
	v_and_b32_e32 v171, 0xffff0000, v149
	v_pk_add_f32 v[168:169], v[96:97], v[168:169]
	v_pk_add_f32 v[170:171], v[98:99], v[170:171]
	v_cvt_pk_bf16_f32 v148, v168, v169
	v_cvt_pk_bf16_f32 v149, v170, v171
	v_lshlrev_b32_e32 v168, 16, v150
	v_and_b32_e32 v169, 0xffff0000, v150
	v_lshlrev_b32_e32 v170, 16, v151
	v_and_b32_e32 v171, 0xffff0000, v151
	v_pk_add_f32 v[168:169], v[100:101], v[168:169]
	v_pk_add_f32 v[170:171], v[102:103], v[170:171]
	v_cvt_pk_bf16_f32 v150, v168, v169
	v_cvt_pk_bf16_f32 v151, v170, v171
	ds_write_b128 v67, v[148:151] offset:11296
	s_waitcnt vmcnt(3)
	v_lshlrev_b32_e32 v168, 16, v152
	v_and_b32_e32 v169, 0xffff0000, v152
	v_lshlrev_b32_e32 v170, 16, v153
	v_and_b32_e32 v171, 0xffff0000, v153
	v_pk_add_f32 v[168:169], v[72:73], v[168:169]
	v_pk_add_f32 v[170:171], v[74:75], v[170:171]
	v_cvt_pk_bf16_f32 v152, v168, v169
	v_cvt_pk_bf16_f32 v153, v170, v171
	v_lshlrev_b32_e32 v168, 16, v154
	v_and_b32_e32 v169, 0xffff0000, v154
	v_lshlrev_b32_e32 v170, 16, v155
	v_and_b32_e32 v171, 0xffff0000, v155
	v_pk_add_f32 v[168:169], v[76:77], v[168:169]
	v_pk_add_f32 v[170:171], v[78:79], v[170:171]
	v_cvt_pk_bf16_f32 v154, v168, v169
	v_cvt_pk_bf16_f32 v155, v170, v171
	ds_write_b128 v67, v[152:155] offset:12336
	s_waitcnt vmcnt(2)
	v_lshlrev_b32_e32 v168, 16, v156
	v_and_b32_e32 v169, 0xffff0000, v156
	v_lshlrev_b32_e32 v170, 16, v157
	v_and_b32_e32 v171, 0xffff0000, v157
	v_pk_add_f32 v[168:169], v[80:81], v[168:169]
	v_pk_add_f32 v[170:171], v[82:83], v[170:171]
	v_cvt_pk_bf16_f32 v156, v168, v169
	v_cvt_pk_bf16_f32 v157, v170, v171
	v_lshlrev_b32_e32 v168, 16, v158
	v_and_b32_e32 v169, 0xffff0000, v158
	v_lshlrev_b32_e32 v170, 16, v159
	v_and_b32_e32 v171, 0xffff0000, v159
	v_pk_add_f32 v[168:169], v[84:85], v[168:169]
	v_pk_add_f32 v[170:171], v[86:87], v[170:171]
	v_cvt_pk_bf16_f32 v158, v168, v169
	v_cvt_pk_bf16_f32 v159, v170, v171
	ds_write_b128 v67, v[156:159] offset:13360
	s_waitcnt vmcnt(1)
	v_lshlrev_b32_e32 v168, 16, v160
	v_and_b32_e32 v169, 0xffff0000, v160
	v_lshlrev_b32_e32 v170, 16, v161
	v_and_b32_e32 v171, 0xffff0000, v161
	v_pk_add_f32 v[168:169], v[88:89], v[168:169]
	v_pk_add_f32 v[170:171], v[90:91], v[170:171]
	v_cvt_pk_bf16_f32 v160, v168, v169
	v_cvt_pk_bf16_f32 v161, v170, v171
	v_lshlrev_b32_e32 v168, 16, v162
	v_and_b32_e32 v169, 0xffff0000, v162
	v_lshlrev_b32_e32 v170, 16, v163
	v_and_b32_e32 v171, 0xffff0000, v163
	v_pk_add_f32 v[168:169], v[92:93], v[168:169]
	v_pk_add_f32 v[170:171], v[94:95], v[170:171]
	v_cvt_pk_bf16_f32 v162, v168, v169
	v_cvt_pk_bf16_f32 v163, v170, v171
	ds_write_b128 v67, v[160:163] offset:14384
	s_waitcnt vmcnt(0)
	v_lshlrev_b32_e32 v168, 16, v164
	v_and_b32_e32 v169, 0xffff0000, v164
	v_lshlrev_b32_e32 v170, 16, v165
	v_and_b32_e32 v171, 0xffff0000, v165
	v_pk_add_f32 v[168:169], v[96:97], v[168:169]
	v_pk_add_f32 v[170:171], v[98:99], v[170:171]
	v_cvt_pk_bf16_f32 v164, v168, v169
	v_cvt_pk_bf16_f32 v165, v170, v171
	v_lshlrev_b32_e32 v168, 16, v166
	v_and_b32_e32 v169, 0xffff0000, v166
	v_lshlrev_b32_e32 v170, 16, v167
	v_and_b32_e32 v171, 0xffff0000, v167
	v_pk_add_f32 v[168:169], v[100:101], v[168:169]
	v_pk_add_f32 v[170:171], v[102:103], v[170:171]
	v_cvt_pk_bf16_f32 v166, v168, v169
	v_cvt_pk_bf16_f32 v167, v170, v171
	ds_write_b128 v67, v[164:167] offset:15408
	v_lshl_add_u64 v[70:71], v[38:39], 0, v[0:1]
	v_mul_u32_u24_e32 v69, 0x1010, v41
	v_add_u32_e32 v69, v69, v0
	v_add_u32_e32 v69, 0x7000, v69
	global_load_dwordx4 v[72:75], v[70:71], off offset:-128
	global_load_dwordx4 v[76:79], v[70:71], off offset:-96
	global_load_dwordx4 v[80:83], v[70:71], off offset:-64
	global_load_dwordx4 v[84:87], v[70:71], off offset:-32
	global_load_dwordx4 v[88:91], v[70:71], off
	global_load_dwordx4 v[92:95], v[70:71], off offset:32
	global_load_dwordx4 v[96:99], v[70:71], off offset:64
	global_load_dwordx4 v[100:103], v[70:71], off offset:96
	global_load_dwordx4 v[168:171], v[70:71], off offset:128
	global_load_dwordx4 v[172:175], v[70:71], off offset:160
	global_load_dwordx4 v[176:179], v[70:71], off offset:192
	global_load_dwordx4 v[180:183], v[70:71], off offset:224
	global_load_dwordx4 v[184:187], v[70:71], off offset:256
	global_load_dwordx4 v[188:191], v[70:71], off offset:288
	global_load_dwordx4 v[192:195], v[70:71], off offset:320
	global_load_dwordx4 v[196:199], v[70:71], off offset:352
	s_waitcnt lgkmcnt(0)
	s_barrier
; #define LAS __attribute__((address_space(3)))
; __device__ __forceinline__ v16f mfma32(v8s a, v8s b, v16f c) { return __builtin_amdgcn_mfma_f32_32x32x16_bf16(a, b, c, 0, 0, 0); }
; __device__ __forceinline__ void compress_unit(LAS unsigned char* lds, int u, const bf16_t* QKV, const float* pe_k, const float* pe_v,
;                                               const bf16_t* CW1  , const bf16_t* CW2  , bf16_t* KCMP, bf16_t* VCMP) {
;     ...
;     for (int st = 0; st < 128; ++st) {
;         const int li = st >> 2, d0 = (st & 3) * 16;
;         const v4u ar = *(const v4u*)(Ag + (size_t)li * EVEN_PAD + d0);
;         const v4f pa = *(const LAS v4f*)(PE + li * 64 + d0 + hi * 8), pb = *(const LAS v4f*)(PE + li * 64 + d0 + hi * 8 + 4);
;         const v8s bfr = *(const v8s*)(Bg + st * 16);
;         v4u aw;
;         aw.x = pkbf(__uint_as_float(ar.x << 16) + pa.x, __uint_as_float(ar.x & 0xffff0000u) + pa.y);
;         aw.y = pkbf(__uint_as_float(ar.y << 16) + pa.z, __uint_as_float(ar.y & 0xffff0000u) + pa.w);
;         aw.z = pkbf(__uint_as_float(ar.z << 16) + pb.x, __uint_as_float(ar.z & 0xffff0000u) + pb.y);
;         aw.w = pkbf(__uint_as_float(ar.w << 16) + pb.z, __uint_as_float(ar.w & 0xffff0000u) + pb.w);
;         acc = mfma32(__builtin_bit_cast(v8s, aw), bfr, acc);
;     }
	ds_read_b128 v[104:107], v69
	ds_read_b128 v[108:111], v69 offset:32
	ds_read_b128 v[112:115], v69 offset:64
	ds_read_b128 v[116:119], v69 offset:96
	ds_read_b128 v[120:123], v69 offset:128
	ds_read_b128 v[124:127], v69 offset:160
	ds_read_b128 v[128:131], v69 offset:192
	ds_read_b128 v[132:135], v69 offset:224
	ds_read_b128 v[136:139], v69 offset:256
	ds_read_b128 v[140:143], v69 offset:288
	ds_read_b128 v[144:147], v69 offset:320
	ds_read_b128 v[148:151], v69 offset:352
	ds_read_b128 v[152:155], v69 offset:384
	ds_read_b128 v[156:159], v69 offset:416
	ds_read_b128 v[160:163], v69 offset:448
	ds_read_b128 v[164:167], v69 offset:480
	s_waitcnt lgkmcnt(8)
	s_waitcnt vmcnt(15)
	v_mfma_f32_32x32x16_bf16 v[2:17], v[104:107], v[72:75], v[2:17]
	s_waitcnt vmcnt(14)
	v_mfma_f32_32x32x16_bf16 v[2:17], v[108:111], v[76:79], v[2:17]
	s_waitcnt vmcnt(13)
	v_mfma_f32_32x32x16_bf16 v[2:17], v[112:115], v[80:83], v[2:17]
	s_waitcnt vmcnt(12)
	v_mfma_f32_32x32x16_bf16 v[2:17], v[116:119], v[84:87], v[2:17]
	s_waitcnt vmcnt(11)
	v_mfma_f32_32x32x16_bf16 v[2:17], v[120:123], v[88:91], v[2:17]
	s_waitcnt vmcnt(10)
	v_mfma_f32_32x32x16_bf16 v[2:17], v[124:127], v[92:95], v[2:17]
	s_waitcnt vmcnt(9)
	v_mfma_f32_32x32x16_bf16 v[2:17], v[128:131], v[96:99], v[2:17]
	s_waitcnt vmcnt(8)
	v_mfma_f32_32x32x16_bf16 v[2:17], v[132:135], v[100:103], v[2:17]
	global_load_dwordx4 v[72:75], v[70:71], off offset:384
	global_load_dwordx4 v[76:79], v[70:71], off offset:416
	global_load_dwordx4 v[80:83], v[70:71], off offset:448
	global_load_dwordx4 v[84:87], v[70:71], off offset:480
	global_load_dwordx4 v[88:91], v[70:71], off offset:512
	global_load_dwordx4 v[92:95], v[70:71], off offset:544
	global_load_dwordx4 v[96:99], v[70:71], off offset:576
	global_load_dwordx4 v[100:103], v[70:71], off offset:608
	ds_read_b128 v[104:107], v69 offset:512
	ds_read_b128 v[108:111], v69 offset:544
	ds_read_b128 v[112:115], v69 offset:576
	ds_read_b128 v[116:119], v69 offset:608
	ds_read_b128 v[120:123], v69 offset:640
	ds_read_b128 v[124:127], v69 offset:672
	ds_read_b128 v[128:131], v69 offset:704
	ds_read_b128 v[132:135], v69 offset:736
	s_waitcnt lgkmcnt(8)
	s_waitcnt vmcnt(15)
	v_mfma_f32_32x32x16_bf16 v[2:17], v[136:139], v[168:171], v[2:17]
	s_waitcnt vmcnt(14)
	v_mfma_f32_32x32x16_bf16 v[2:17], v[140:143], v[172:175], v[2:17]
	s_waitcnt vmcnt(13)
	v_mfma_f32_32x32x16_bf16 v[2:17], v[144:147], v[176:179], v[2:17]
	s_waitcnt vmcnt(12)
	v_mfma_f32_32x32x16_bf16 v[2:17], v[148:151], v[180:183], v[2:17]
	s_waitcnt vmcnt(11)
	v_mfma_f32_32x32x16_bf16 v[2:17], v[152:155], v[184:187], v[2:17]
	s_waitcnt vmcnt(10)
	v_mfma_f32_32x32x16_bf16 v[2:17], v[156:159], v[188:191], v[2:17]
	s_waitcnt vmcnt(9)
	v_mfma_f32_32x32x16_bf16 v[2:17], v[160:163], v[192:195], v[2:17]
	s_waitcnt vmcnt(8)
	v_mfma_f32_32x32x16_bf16 v[2:17], v[164:167], v[196:199], v[2:17]
	global_load_dwordx4 v[168:171], v[70:71], off offset:640
	global_load_dwordx4 v[172:175], v[70:71], off offset:672
	global_load_dwordx4 v[176:179], v[70:71], off offset:704
	global_load_dwordx4 v[180:183], v[70:71], off offset:736
	global_load_dwordx4 v[184:187], v[70:71], off offset:768
	global_load_dwordx4 v[188:191], v[70:71], off offset:800
	global_load_dwordx4 v[192:195], v[70:71], off offset:832
	global_load_dwordx4 v[196:199], v[70:71], off offset:864
	ds_read_b128 v[136:139], v69 offset:768
	ds_read_b128 v[140:143], v69 offset:800
	ds_read_b128 v[144:147], v69 offset:832
	ds_read_b128 v[148:151], v69 offset:864
	ds_read_b128 v[152:155], v69 offset:896
	ds_read_b128 v[156:159], v69 offset:928
	ds_read_b128 v[160:163], v69 offset:960
	ds_read_b128 v[164:167], v69 offset:992
	s_waitcnt lgkmcnt(8)
	s_waitcnt vmcnt(15)
	v_mfma_f32_32x32x16_bf16 v[2:17], v[104:107], v[72:75], v[2:17]
	s_waitcnt vmcnt(14)
	v_mfma_f32_32x32x16_bf16 v[2:17], v[108:111], v[76:79], v[2:17]
	s_waitcnt vmcnt(13)
	v_mfma_f32_32x32x16_bf16 v[2:17], v[112:115], v[80:83], v[2:17]
	s_waitcnt vmcnt(12)
	v_mfma_f32_32x32x16_bf16 v[2:17], v[116:119], v[84:87], v[2:17]
	s_waitcnt vmcnt(11)
	v_mfma_f32_32x32x16_bf16 v[2:17], v[120:123], v[88:91], v[2:17]
	s_waitcnt vmcnt(10)
	v_mfma_f32_32x32x16_bf16 v[2:17], v[124:127], v[92:95], v[2:17]
	s_waitcnt vmcnt(9)
	v_mfma_f32_32x32x16_bf16 v[2:17], v[128:131], v[96:99], v[2:17]
	s_waitcnt vmcnt(8)
	v_mfma_f32_32x32x16_bf16 v[2:17], v[132:135], v[100:103], v[2:17]
	global_load_dwordx4 v[72:75], v[70:71], off offset:896
	global_load_dwordx4 v[76:79], v[70:71], off offset:928
	global_load_dwordx4 v[80:83], v[70:71], off offset:960
	global_load_dwordx4 v[84:87], v[70:71], off offset:992
	global_load_dwordx4 v[88:91], v[70:71], off offset:1024
	global_load_dwordx4 v[92:95], v[70:71], off offset:1056
	global_load_dwordx4 v[96:99], v[70:71], off offset:1088
	global_load_dwordx4 v[100:103], v[70:71], off offset:1120
	ds_read_b128 v[104:107], v69 offset:1024
	ds_read_b128 v[108:111], v69 offset:1056
	ds_read_b128 v[112:115], v69 offset:1088
	ds_read_b128 v[116:119], v69 offset:1120
	ds_read_b128 v[120:123], v69 offset:1152
	ds_read_b128 v[124:127], v69 offset:1184
	ds_read_b128 v[128:131], v69 offset:1216
	ds_read_b128 v[132:135], v69 offset:1248
	s_waitcnt lgkmcnt(8)
	s_waitcnt vmcnt(15)
	v_mfma_f32_32x32x16_bf16 v[2:17], v[136:139], v[168:171], v[2:17]
	s_waitcnt vmcnt(14)
	v_mfma_f32_32x32x16_bf16 v[2:17], v[140:143], v[172:175], v[2:17]
	s_waitcnt vmcnt(13)
	v_mfma_f32_32x32x16_bf16 v[2:17], v[144:147], v[176:179], v[2:17]
	s_waitcnt vmcnt(12)
	v_mfma_f32_32x32x16_bf16 v[2:17], v[148:151], v[180:183], v[2:17]
	s_waitcnt vmcnt(11)
	v_mfma_f32_32x32x16_bf16 v[2:17], v[152:155], v[184:187], v[2:17]
	s_waitcnt vmcnt(10)
; #define LAS __attribute__((address_space(3)))
; __device__ __forceinline__ v16f mfma32(v8s a, v8s b, v16f c) { return __builtin_amdgcn_mfma_f32_32x32x16_bf16(a, b, c, 0, 0, 0); }
; __device__ __forceinline__ void compress_unit(LAS unsigned char* lds, int u, const bf16_t* QKV, const float* pe_k, const float* pe_v,
;                                               const bf16_t* CW1  , const bf16_t* CW2  , bf16_t* KCMP, bf16_t* VCMP) {
;     ...
;     for (int st = 0; st < 128; ++st) {
;         const int li = st >> 2, d0 = (st & 3) * 16;
;         const v4u ar = *(const v4u*)(Ag + (size_t)li * EVEN_PAD + d0);
;         const v4f pa = *(const LAS v4f*)(PE + li * 64 + d0 + hi * 8), pb = *(const LAS v4f*)(PE + li * 64 + d0 + hi * 8 + 4);
;         const v8s bfr = *(const v8s*)(Bg + st * 16);
;         v4u aw;
;         aw.x = pkbf(__uint_as_float(ar.x << 16) + pa.x, __uint_as_float(ar.x & 0xffff0000u) + pa.y);
;         aw.y = pkbf(__uint_as_float(ar.y << 16) + pa.z, __uint_as_float(ar.y & 0xffff0000u) + pa.w);
;         aw.z = pkbf(__uint_as_float(ar.z << 16) + pb.x, __uint_as_float(ar.z & 0xffff0000u) + pb.y);
;         aw.w = pkbf(__uint_as_float(ar.w << 16) + pb.z, __uint_as_float(ar.w & 0xffff0000u) + pb.w);
;         acc = mfma32(__builtin_bit_cast(v8s, aw), bfr, acc);
;     }
	v_mfma_f32_32x32x16_bf16 v[2:17], v[156:159], v[188:191], v[2:17]
	s_waitcnt vmcnt(9)
	v_mfma_f32_32x32x16_bf16 v[2:17], v[160:163], v[192:195], v[2:17]
	s_waitcnt vmcnt(8)
	v_mfma_f32_32x32x16_bf16 v[2:17], v[164:167], v[196:199], v[2:17]
	global_load_dwordx4 v[168:171], v[70:71], off offset:1152
	global_load_dwordx4 v[172:175], v[70:71], off offset:1184
	global_load_dwordx4 v[176:179], v[70:71], off offset:1216
	global_load_dwordx4 v[180:183], v[70:71], off offset:1248
	global_load_dwordx4 v[184:187], v[70:71], off offset:1280
	global_load_dwordx4 v[188:191], v[70:71], off offset:1312
	global_load_dwordx4 v[192:195], v[70:71], off offset:1344
	global_load_dwordx4 v[196:199], v[70:71], off offset:1376
	ds_read_b128 v[136:139], v69 offset:1280
	ds_read_b128 v[140:143], v69 offset:1312
	ds_read_b128 v[144:147], v69 offset:1344
	ds_read_b128 v[148:151], v69 offset:1376
	ds_read_b128 v[152:155], v69 offset:1408
	ds_read_b128 v[156:159], v69 offset:1440
	ds_read_b128 v[160:163], v69 offset:1472
	ds_read_b128 v[164:167], v69 offset:1504
	s_waitcnt lgkmcnt(8)
	s_waitcnt vmcnt(15)
	v_mfma_f32_32x32x16_bf16 v[2:17], v[104:107], v[72:75], v[2:17]
	s_waitcnt vmcnt(14)
	v_mfma_f32_32x32x16_bf16 v[2:17], v[108:111], v[76:79], v[2:17]
	s_waitcnt vmcnt(13)
	v_mfma_f32_32x32x16_bf16 v[2:17], v[112:115], v[80:83], v[2:17]
	s_waitcnt vmcnt(12)
	v_mfma_f32_32x32x16_bf16 v[2:17], v[116:119], v[84:87], v[2:17]
	s_waitcnt vmcnt(11)
	v_mfma_f32_32x32x16_bf16 v[2:17], v[120:123], v[88:91], v[2:17]
	s_waitcnt vmcnt(10)
	v_mfma_f32_32x32x16_bf16 v[2:17], v[124:127], v[92:95], v[2:17]
	s_waitcnt vmcnt(9)
	v_mfma_f32_32x32x16_bf16 v[2:17], v[128:131], v[96:99], v[2:17]
	s_waitcnt vmcnt(8)
	v_mfma_f32_32x32x16_bf16 v[2:17], v[132:135], v[100:103], v[2:17]
	global_load_dwordx4 v[72:75], v[70:71], off offset:1408
	global_load_dwordx4 v[76:79], v[70:71], off offset:1440
	global_load_dwordx4 v[80:83], v[70:71], off offset:1472
	global_load_dwordx4 v[84:87], v[70:71], off offset:1504
	global_load_dwordx4 v[88:91], v[70:71], off offset:1536
	global_load_dwordx4 v[92:95], v[70:71], off offset:1568
	global_load_dwordx4 v[96:99], v[70:71], off offset:1600
	global_load_dwordx4 v[100:103], v[70:71], off offset:1632
	ds_read_b128 v[104:107], v69 offset:1536
	ds_read_b128 v[108:111], v69 offset:1568
	ds_read_b128 v[112:115], v69 offset:1600
	ds_read_b128 v[116:119], v69 offset:1632
	ds_read_b128 v[120:123], v69 offset:1664
	ds_read_b128 v[124:127], v69 offset:1696
	ds_read_b128 v[128:131], v69 offset:1728
	ds_read_b128 v[132:135], v69 offset:1760
	s_waitcnt lgkmcnt(8)
	s_waitcnt vmcnt(15)
	v_mfma_f32_32x32x16_bf16 v[2:17], v[136:139], v[168:171], v[2:17]
	s_waitcnt vmcnt(14)
	v_mfma_f32_32x32x16_bf16 v[2:17], v[140:143], v[172:175], v[2:17]
	s_waitcnt vmcnt(13)
	v_mfma_f32_32x32x16_bf16 v[2:17], v[144:147], v[176:179], v[2:17]
	s_waitcnt vmcnt(12)
	v_mfma_f32_32x32x16_bf16 v[2:17], v[148:151], v[180:183], v[2:17]
	s_waitcnt vmcnt(11)
	v_mfma_f32_32x32x16_bf16 v[2:17], v[152:155], v[184:187], v[2:17]
	s_waitcnt vmcnt(10)
	v_mfma_f32_32x32x16_bf16 v[2:17], v[156:159], v[188:191], v[2:17]
	s_waitcnt vmcnt(9)
	v_mfma_f32_32x32x16_bf16 v[2:17], v[160:163], v[192:195], v[2:17]
	s_waitcnt vmcnt(8)
	v_mfma_f32_32x32x16_bf16 v[2:17], v[164:167], v[196:199], v[2:17]
	global_load_dwordx4 v[168:171], v[70:71], off offset:1664
	global_load_dwordx4 v[172:175], v[70:71], off offset:1696
	global_load_dwordx4 v[176:179], v[70:71], off offset:1728
	global_load_dwordx4 v[180:183], v[70:71], off offset:1760
	global_load_dwordx4 v[184:187], v[70:71], off offset:1792
	global_load_dwordx4 v[188:191], v[70:71], off offset:1824
	global_load_dwordx4 v[192:195], v[70:71], off offset:1856
	global_load_dwordx4 v[196:199], v[70:71], off offset:1888
	ds_read_b128 v[136:139], v69 offset:1792
	ds_read_b128 v[140:143], v69 offset:1824
	ds_read_b128 v[144:147], v69 offset:1856
	ds_read_b128 v[148:151], v69 offset:1888
	ds_read_b128 v[152:155], v69 offset:1920
	ds_read_b128 v[156:159], v69 offset:1952
	ds_read_b128 v[160:163], v69 offset:1984
	ds_read_b128 v[164:167], v69 offset:2016
	s_waitcnt lgkmcnt(8)
	s_waitcnt vmcnt(15)
	v_mfma_f32_32x32x16_bf16 v[2:17], v[104:107], v[72:75], v[2:17]
	s_waitcnt vmcnt(14)
	v_mfma_f32_32x32x16_bf16 v[2:17], v[108:111], v[76:79], v[2:17]
	s_waitcnt vmcnt(13)
	v_mfma_f32_32x32x16_bf16 v[2:17], v[112:115], v[80:83], v[2:17]
	s_waitcnt vmcnt(12)
	v_mfma_f32_32x32x16_bf16 v[2:17], v[116:119], v[84:87], v[2:17]
	s_waitcnt vmcnt(11)
	v_mfma_f32_32x32x16_bf16 v[2:17], v[120:123], v[88:91], v[2:17]
	s_waitcnt vmcnt(10)
	v_mfma_f32_32x32x16_bf16 v[2:17], v[124:127], v[92:95], v[2:17]
	s_waitcnt vmcnt(9)
	v_mfma_f32_32x32x16_bf16 v[2:17], v[128:131], v[96:99], v[2:17]
	s_waitcnt vmcnt(8)
	v_mfma_f32_32x32x16_bf16 v[2:17], v[132:135], v[100:103], v[2:17]
	global_load_dwordx4 v[72:75], v[70:71], off offset:1920
	global_load_dwordx4 v[76:79], v[70:71], off offset:1952
	global_load_dwordx4 v[80:83], v[70:71], off offset:1984
	global_load_dwordx4 v[84:87], v[70:71], off offset:2016
	global_load_dwordx4 v[88:91], v[70:71], off offset:2048
	global_load_dwordx4 v[92:95], v[70:71], off offset:2080
	global_load_dwordx4 v[96:99], v[70:71], off offset:2112
	global_load_dwordx4 v[100:103], v[70:71], off offset:2144
	ds_read_b128 v[104:107], v69 offset:2048
	ds_read_b128 v[108:111], v69 offset:2080
	ds_read_b128 v[112:115], v69 offset:2112
	ds_read_b128 v[116:119], v69 offset:2144
	ds_read_b128 v[120:123], v69 offset:2176
	ds_read_b128 v[124:127], v69 offset:2208
	ds_read_b128 v[128:131], v69 offset:2240
	ds_read_b128 v[132:135], v69 offset:2272
	s_waitcnt lgkmcnt(8)
	s_waitcnt vmcnt(15)
; #define LAS __attribute__((address_space(3)))
; __device__ __forceinline__ v16f mfma32(v8s a, v8s b, v16f c) { return __builtin_amdgcn_mfma_f32_32x32x16_bf16(a, b, c, 0, 0, 0); }
; __device__ __forceinline__ void compress_unit(LAS unsigned char* lds, int u, const bf16_t* QKV, const float* pe_k, const float* pe_v,
;                                               const bf16_t* CW1  , const bf16_t* CW2  , bf16_t* KCMP, bf16_t* VCMP) {
;     ...
;     for (int st = 0; st < 128; ++st) {
;         const int li = st >> 2, d0 = (st & 3) * 16;
;         const v4u ar = *(const v4u*)(Ag + (size_t)li * EVEN_PAD + d0);
;         const v4f pa = *(const LAS v4f*)(PE + li * 64 + d0 + hi * 8), pb = *(const LAS v4f*)(PE + li * 64 + d0 + hi * 8 + 4);
;         const v8s bfr = *(const v8s*)(Bg + st * 16);
;         v4u aw;
;         aw.x = pkbf(__uint_as_float(ar.x << 16) + pa.x, __uint_as_float(ar.x & 0xffff0000u) + pa.y);
;         aw.y = pkbf(__uint_as_float(ar.y << 16) + pa.z, __uint_as_float(ar.y & 0xffff0000u) + pa.w);
;         aw.z = pkbf(__uint_as_float(ar.z << 16) + pb.x, __uint_as_float(ar.z & 0xffff0000u) + pb.y);
;         aw.w = pkbf(__uint_as_float(ar.w << 16) + pb.z, __uint_as_float(ar.w & 0xffff0000u) + pb.w);
;         acc = mfma32(__builtin_bit_cast(v8s, aw), bfr, acc);
;     }
	v_mfma_f32_32x32x16_bf16 v[2:17], v[136:139], v[168:171], v[2:17]
	s_waitcnt vmcnt(14)
	v_mfma_f32_32x32x16_bf16 v[2:17], v[140:143], v[172:175], v[2:17]
	s_waitcnt vmcnt(13)
	v_mfma_f32_32x32x16_bf16 v[2:17], v[144:147], v[176:179], v[2:17]
	s_waitcnt vmcnt(12)
	v_mfma_f32_32x32x16_bf16 v[2:17], v[148:151], v[180:183], v[2:17]
	s_waitcnt vmcnt(11)
	v_mfma_f32_32x32x16_bf16 v[2:17], v[152:155], v[184:187], v[2:17]
	s_waitcnt vmcnt(10)
	v_mfma_f32_32x32x16_bf16 v[2:17], v[156:159], v[188:191], v[2:17]
	s_waitcnt vmcnt(9)
	v_mfma_f32_32x32x16_bf16 v[2:17], v[160:163], v[192:195], v[2:17]
	s_waitcnt vmcnt(8)
	v_mfma_f32_32x32x16_bf16 v[2:17], v[164:167], v[196:199], v[2:17]
	global_load_dwordx4 v[168:171], v[70:71], off offset:2176
	global_load_dwordx4 v[172:175], v[70:71], off offset:2208
	global_load_dwordx4 v[176:179], v[70:71], off offset:2240
	global_load_dwordx4 v[180:183], v[70:71], off offset:2272
	global_load_dwordx4 v[184:187], v[70:71], off offset:2304
	global_load_dwordx4 v[188:191], v[70:71], off offset:2336
	global_load_dwordx4 v[192:195], v[70:71], off offset:2368
	global_load_dwordx4 v[196:199], v[70:71], off offset:2400
	ds_read_b128 v[136:139], v69 offset:2304
	ds_read_b128 v[140:143], v69 offset:2336
	ds_read_b128 v[144:147], v69 offset:2368
	ds_read_b128 v[148:151], v69 offset:2400
	ds_read_b128 v[152:155], v69 offset:2432
	ds_read_b128 v[156:159], v69 offset:2464
	ds_read_b128 v[160:163], v69 offset:2496
	ds_read_b128 v[164:167], v69 offset:2528
	s_waitcnt lgkmcnt(8)
	s_waitcnt vmcnt(15)
	v_mfma_f32_32x32x16_bf16 v[2:17], v[104:107], v[72:75], v[2:17]
	s_waitcnt vmcnt(14)
	v_mfma_f32_32x32x16_bf16 v[2:17], v[108:111], v[76:79], v[2:17]
	s_waitcnt vmcnt(13)
	v_mfma_f32_32x32x16_bf16 v[2:17], v[112:115], v[80:83], v[2:17]
	s_waitcnt vmcnt(12)
	v_mfma_f32_32x32x16_bf16 v[2:17], v[116:119], v[84:87], v[2:17]
	s_waitcnt vmcnt(11)
	v_mfma_f32_32x32x16_bf16 v[2:17], v[120:123], v[88:91], v[2:17]
	s_waitcnt vmcnt(10)
	v_mfma_f32_32x32x16_bf16 v[2:17], v[124:127], v[92:95], v[2:17]
	s_waitcnt vmcnt(9)
	v_mfma_f32_32x32x16_bf16 v[2:17], v[128:131], v[96:99], v[2:17]
	s_waitcnt vmcnt(8)
	v_mfma_f32_32x32x16_bf16 v[2:17], v[132:135], v[100:103], v[2:17]
	global_load_dwordx4 v[72:75], v[70:71], off offset:2432
	global_load_dwordx4 v[76:79], v[70:71], off offset:2464
	global_load_dwordx4 v[80:83], v[70:71], off offset:2496
	global_load_dwordx4 v[84:87], v[70:71], off offset:2528
	global_load_dwordx4 v[88:91], v[70:71], off offset:2560
	global_load_dwordx4 v[92:95], v[70:71], off offset:2592
	global_load_dwordx4 v[96:99], v[70:71], off offset:2624
	global_load_dwordx4 v[100:103], v[70:71], off offset:2656
	ds_read_b128 v[104:107], v69 offset:2560
	ds_read_b128 v[108:111], v69 offset:2592
	ds_read_b128 v[112:115], v69 offset:2624
	ds_read_b128 v[116:119], v69 offset:2656
	ds_read_b128 v[120:123], v69 offset:2688
	ds_read_b128 v[124:127], v69 offset:2720
	ds_read_b128 v[128:131], v69 offset:2752
	ds_read_b128 v[132:135], v69 offset:2784
	s_waitcnt lgkmcnt(8)
	s_waitcnt vmcnt(15)
	v_mfma_f32_32x32x16_bf16 v[2:17], v[136:139], v[168:171], v[2:17]
	s_waitcnt vmcnt(14)
	v_mfma_f32_32x32x16_bf16 v[2:17], v[140:143], v[172:175], v[2:17]
	s_waitcnt vmcnt(13)
	v_mfma_f32_32x32x16_bf16 v[2:17], v[144:147], v[176:179], v[2:17]
	s_waitcnt vmcnt(12)
	v_mfma_f32_32x32x16_bf16 v[2:17], v[148:151], v[180:183], v[2:17]
	s_waitcnt vmcnt(11)
	v_mfma_f32_32x32x16_bf16 v[2:17], v[152:155], v[184:187], v[2:17]
	s_waitcnt vmcnt(10)
	v_mfma_f32_32x32x16_bf16 v[2:17], v[156:159], v[188:191], v[2:17]
	s_waitcnt vmcnt(9)
	v_mfma_f32_32x32x16_bf16 v[2:17], v[160:163], v[192:195], v[2:17]
	s_waitcnt vmcnt(8)
	v_mfma_f32_32x32x16_bf16 v[2:17], v[164:167], v[196:199], v[2:17]
	global_load_dwordx4 v[168:171], v[70:71], off offset:2688
	global_load_dwordx4 v[172:175], v[70:71], off offset:2720
	global_load_dwordx4 v[176:179], v[70:71], off offset:2752
	global_load_dwordx4 v[180:183], v[70:71], off offset:2784
	global_load_dwordx4 v[184:187], v[70:71], off offset:2816
	global_load_dwordx4 v[188:191], v[70:71], off offset:2848
	global_load_dwordx4 v[192:195], v[70:71], off offset:2880
	global_load_dwordx4 v[196:199], v[70:71], off offset:2912
	ds_read_b128 v[136:139], v69 offset:2816
	ds_read_b128 v[140:143], v69 offset:2848
	ds_read_b128 v[144:147], v69 offset:2880
	ds_read_b128 v[148:151], v69 offset:2912
	ds_read_b128 v[152:155], v69 offset:2944
	ds_read_b128 v[156:159], v69 offset:2976
	ds_read_b128 v[160:163], v69 offset:3008
	ds_read_b128 v[164:167], v69 offset:3040
	s_waitcnt lgkmcnt(8)
	s_waitcnt vmcnt(15)
	v_mfma_f32_32x32x16_bf16 v[2:17], v[104:107], v[72:75], v[2:17]
	s_waitcnt vmcnt(14)
	v_mfma_f32_32x32x16_bf16 v[2:17], v[108:111], v[76:79], v[2:17]
	s_waitcnt vmcnt(13)
	v_mfma_f32_32x32x16_bf16 v[2:17], v[112:115], v[80:83], v[2:17]
	s_waitcnt vmcnt(12)
	v_mfma_f32_32x32x16_bf16 v[2:17], v[116:119], v[84:87], v[2:17]
	s_waitcnt vmcnt(11)
	v_mfma_f32_32x32x16_bf16 v[2:17], v[120:123], v[88:91], v[2:17]
	s_waitcnt vmcnt(10)
	v_mfma_f32_32x32x16_bf16 v[2:17], v[124:127], v[92:95], v[2:17]
	s_waitcnt vmcnt(9)
	v_mfma_f32_32x32x16_bf16 v[2:17], v[128:131], v[96:99], v[2:17]
	s_waitcnt vmcnt(8)
	v_mfma_f32_32x32x16_bf16 v[2:17], v[132:135], v[100:103], v[2:17]
	global_load_dwordx4 v[72:75], v[70:71], off offset:2944
	global_load_dwordx4 v[76:79], v[70:71], off offset:2976
	global_load_dwordx4 v[80:83], v[70:71], off offset:3008
	global_load_dwordx4 v[84:87], v[70:71], off offset:3040
	global_load_dwordx4 v[88:91], v[70:71], off offset:3072
	global_load_dwordx4 v[92:95], v[70:71], off offset:3104
	global_load_dwordx4 v[96:99], v[70:71], off offset:3136
	global_load_dwordx4 v[100:103], v[70:71], off offset:3168
	ds_read_b128 v[104:107], v69 offset:3072
	ds_read_b128 v[108:111], v69 offset:3104
	ds_read_b128 v[112:115], v69 offset:3136
	ds_read_b128 v[116:119], v69 offset:3168
	ds_read_b128 v[120:123], v69 offset:3200
	ds_read_b128 v[124:127], v69 offset:3232
	ds_read_b128 v[128:131], v69 offset:3264
	ds_read_b128 v[132:135], v69 offset:3296
	s_waitcnt lgkmcnt(8)
; #define LAS __attribute__((address_space(3)))
; __device__ __forceinline__ v16f mfma32(v8s a, v8s b, v16f c) { return __builtin_amdgcn_mfma_f32_32x32x16_bf16(a, b, c, 0, 0, 0); }
; __device__ __forceinline__ void compress_unit(LAS unsigned char* lds, int u, const bf16_t* QKV, const float* pe_k, const float* pe_v,
;                                               const bf16_t* CW1  , const bf16_t* CW2  , bf16_t* KCMP, bf16_t* VCMP) {
;     ...
;     for (int st = 0; st < 128; ++st) {
;         const int li = st >> 2, d0 = (st & 3) * 16;
;         const v4u ar = *(const v4u*)(Ag + (size_t)li * EVEN_PAD + d0);
;         const v4f pa = *(const LAS v4f*)(PE + li * 64 + d0 + hi * 8), pb = *(const LAS v4f*)(PE + li * 64 + d0 + hi * 8 + 4);
;         const v8s bfr = *(const v8s*)(Bg + st * 16);
;         v4u aw;
;         aw.x = pkbf(__uint_as_float(ar.x << 16) + pa.x, __uint_as_float(ar.x & 0xffff0000u) + pa.y);
;         aw.y = pkbf(__uint_as_float(ar.y << 16) + pa.z, __uint_as_float(ar.y & 0xffff0000u) + pa.w);
;         aw.z = pkbf(__uint_as_float(ar.z << 16) + pb.x, __uint_as_float(ar.z & 0xffff0000u) + pb.y);
;         aw.w = pkbf(__uint_as_float(ar.w << 16) + pb.z, __uint_as_float(ar.w & 0xffff0000u) + pb.w);
;         acc = mfma32(__builtin_bit_cast(v8s, aw), bfr, acc);
;     }
	s_waitcnt vmcnt(15)
	v_mfma_f32_32x32x16_bf16 v[2:17], v[136:139], v[168:171], v[2:17]
	s_waitcnt vmcnt(14)
	v_mfma_f32_32x32x16_bf16 v[2:17], v[140:143], v[172:175], v[2:17]
	s_waitcnt vmcnt(13)
	v_mfma_f32_32x32x16_bf16 v[2:17], v[144:147], v[176:179], v[2:17]
	s_waitcnt vmcnt(12)
	v_mfma_f32_32x32x16_bf16 v[2:17], v[148:151], v[180:183], v[2:17]
	s_waitcnt vmcnt(11)
	v_mfma_f32_32x32x16_bf16 v[2:17], v[152:155], v[184:187], v[2:17]
	s_waitcnt vmcnt(10)
	v_mfma_f32_32x32x16_bf16 v[2:17], v[156:159], v[188:191], v[2:17]
	s_waitcnt vmcnt(9)
	v_mfma_f32_32x32x16_bf16 v[2:17], v[160:163], v[192:195], v[2:17]
	s_waitcnt vmcnt(8)
	v_mfma_f32_32x32x16_bf16 v[2:17], v[164:167], v[196:199], v[2:17]
	global_load_dwordx4 v[168:171], v[70:71], off offset:3200
	global_load_dwordx4 v[172:175], v[70:71], off offset:3232
	global_load_dwordx4 v[176:179], v[70:71], off offset:3264
	global_load_dwordx4 v[180:183], v[70:71], off offset:3296
	global_load_dwordx4 v[184:187], v[70:71], off offset:3328
	global_load_dwordx4 v[188:191], v[70:71], off offset:3360
	global_load_dwordx4 v[192:195], v[70:71], off offset:3392
	global_load_dwordx4 v[196:199], v[70:71], off offset:3424
	ds_read_b128 v[136:139], v69 offset:3328
	ds_read_b128 v[140:143], v69 offset:3360
	ds_read_b128 v[144:147], v69 offset:3392
	ds_read_b128 v[148:151], v69 offset:3424
	ds_read_b128 v[152:155], v69 offset:3456
	ds_read_b128 v[156:159], v69 offset:3488
	ds_read_b128 v[160:163], v69 offset:3520
	ds_read_b128 v[164:167], v69 offset:3552
	s_waitcnt lgkmcnt(8)
	s_waitcnt vmcnt(15)
	v_mfma_f32_32x32x16_bf16 v[2:17], v[104:107], v[72:75], v[2:17]
	s_waitcnt vmcnt(14)
	v_mfma_f32_32x32x16_bf16 v[2:17], v[108:111], v[76:79], v[2:17]
	s_waitcnt vmcnt(13)
	v_mfma_f32_32x32x16_bf16 v[2:17], v[112:115], v[80:83], v[2:17]
	s_waitcnt vmcnt(12)
	v_mfma_f32_32x32x16_bf16 v[2:17], v[116:119], v[84:87], v[2:17]
	s_waitcnt vmcnt(11)
	v_mfma_f32_32x32x16_bf16 v[2:17], v[120:123], v[88:91], v[2:17]
	s_waitcnt vmcnt(10)
	v_mfma_f32_32x32x16_bf16 v[2:17], v[124:127], v[92:95], v[2:17]
	s_waitcnt vmcnt(9)
	v_mfma_f32_32x32x16_bf16 v[2:17], v[128:131], v[96:99], v[2:17]
	s_waitcnt vmcnt(8)
	v_mfma_f32_32x32x16_bf16 v[2:17], v[132:135], v[100:103], v[2:17]
	global_load_dwordx4 v[72:75], v[70:71], off offset:3456
	global_load_dwordx4 v[76:79], v[70:71], off offset:3488
	global_load_dwordx4 v[80:83], v[70:71], off offset:3520
	global_load_dwordx4 v[84:87], v[70:71], off offset:3552
	global_load_dwordx4 v[88:91], v[70:71], off offset:3584
	global_load_dwordx4 v[92:95], v[70:71], off offset:3616
	global_load_dwordx4 v[96:99], v[70:71], off offset:3648
	global_load_dwordx4 v[100:103], v[70:71], off offset:3680
	ds_read_b128 v[104:107], v69 offset:3584
	ds_read_b128 v[108:111], v69 offset:3616
	ds_read_b128 v[112:115], v69 offset:3648
	ds_read_b128 v[116:119], v69 offset:3680
	ds_read_b128 v[120:123], v69 offset:3712
	ds_read_b128 v[124:127], v69 offset:3744
	ds_read_b128 v[128:131], v69 offset:3776
	ds_read_b128 v[132:135], v69 offset:3808
	s_waitcnt lgkmcnt(8)
	s_waitcnt vmcnt(15)
	v_mfma_f32_32x32x16_bf16 v[2:17], v[136:139], v[168:171], v[2:17]
	s_waitcnt vmcnt(14)
	v_mfma_f32_32x32x16_bf16 v[2:17], v[140:143], v[172:175], v[2:17]
	s_waitcnt vmcnt(13)
	v_mfma_f32_32x32x16_bf16 v[2:17], v[144:147], v[176:179], v[2:17]
	s_waitcnt vmcnt(12)
	v_mfma_f32_32x32x16_bf16 v[2:17], v[148:151], v[180:183], v[2:17]
	s_waitcnt vmcnt(11)
	v_mfma_f32_32x32x16_bf16 v[2:17], v[152:155], v[184:187], v[2:17]
	s_waitcnt vmcnt(10)
	v_mfma_f32_32x32x16_bf16 v[2:17], v[156:159], v[188:191], v[2:17]
	s_waitcnt vmcnt(9)
	v_mfma_f32_32x32x16_bf16 v[2:17], v[160:163], v[192:195], v[2:17]
	s_waitcnt vmcnt(8)
	v_mfma_f32_32x32x16_bf16 v[2:17], v[164:167], v[196:199], v[2:17]
	global_load_dwordx4 v[168:171], v[70:71], off offset:3712
	global_load_dwordx4 v[172:175], v[70:71], off offset:3744
	global_load_dwordx4 v[176:179], v[70:71], off offset:3776
	global_load_dwordx4 v[180:183], v[70:71], off offset:3808
	global_load_dwordx4 v[184:187], v[70:71], off offset:3840
	global_load_dwordx4 v[188:191], v[70:71], off offset:3872
	global_load_dwordx4 v[192:195], v[70:71], off offset:3904
	global_load_dwordx4 v[196:199], v[70:71], off offset:3936
	ds_read_b128 v[136:139], v69 offset:3840
	ds_read_b128 v[140:143], v69 offset:3872
	ds_read_b128 v[144:147], v69 offset:3904
	ds_read_b128 v[148:151], v69 offset:3936
	ds_read_b128 v[152:155], v69 offset:3968
	ds_read_b128 v[156:159], v69 offset:4000
	ds_read_b128 v[160:163], v69 offset:4032
	ds_read_b128 v[164:167], v69 offset:4064
	s_waitcnt lgkmcnt(8)
	s_waitcnt vmcnt(15)
	v_mfma_f32_32x32x16_bf16 v[2:17], v[104:107], v[72:75], v[2:17]
	s_waitcnt vmcnt(14)
	v_mfma_f32_32x32x16_bf16 v[2:17], v[108:111], v[76:79], v[2:17]
	s_waitcnt vmcnt(13)
	v_mfma_f32_32x32x16_bf16 v[2:17], v[112:115], v[80:83], v[2:17]
	s_waitcnt vmcnt(12)
	v_mfma_f32_32x32x16_bf16 v[2:17], v[116:119], v[84:87], v[2:17]
	s_waitcnt vmcnt(11)
	v_mfma_f32_32x32x16_bf16 v[2:17], v[120:123], v[88:91], v[2:17]
	s_waitcnt vmcnt(10)
	v_mfma_f32_32x32x16_bf16 v[2:17], v[124:127], v[92:95], v[2:17]
	s_waitcnt vmcnt(9)
	v_mfma_f32_32x32x16_bf16 v[2:17], v[128:131], v[96:99], v[2:17]
	s_waitcnt vmcnt(8)
	v_mfma_f32_32x32x16_bf16 v[2:17], v[132:135], v[100:103], v[2:17]
	s_waitcnt lgkmcnt(0)
	s_waitcnt vmcnt(7)
	v_mfma_f32_32x32x16_bf16 v[2:17], v[136:139], v[168:171], v[2:17]
	s_waitcnt vmcnt(6)
	v_mfma_f32_32x32x16_bf16 v[2:17], v[140:143], v[172:175], v[2:17]
	s_waitcnt vmcnt(5)
	v_mfma_f32_32x32x16_bf16 v[2:17], v[144:147], v[176:179], v[2:17]
	s_waitcnt vmcnt(4)
	v_mfma_f32_32x32x16_bf16 v[2:17], v[148:151], v[180:183], v[2:17]
	s_waitcnt vmcnt(3)
; __device__ __forceinline__ int crow(int r, int hi) { return (r & 3) + 8 * (r >> 2) + 4 * hi; }
; __device__ __forceinline__ v16f mfma32(v8s a, v8s b, v16f c) { return __builtin_amdgcn_mfma_f32_32x32x16_bf16(a, b, c, 0, 0, 0); }
; __device__ __forceinline__ float gelu_tanh(float x) {
;     const float u = 0.7978845608028654f * (x + 0.044715f * x * x * x);
;     const float t = 1.f - 2.f / (1.f + __expf(2.f * u));
;     return 0.5f * x * (1.f + t);
; }
; __device__ __forceinline__ void compress_unit(LAS unsigned char* lds, int u, const bf16_t* QKV, const float* pe_k, const float* pe_v,
;                                               const bf16_t* CW1  , const bf16_t* CW2  , bf16_t* KCMP, bf16_t* VCMP) {
;     ...
;         acc = mfma32(__builtin_bit_cast(v8s, aw), bfr, acc);
;     }
; #pragma unroll
;     for (int r = 0; r < 16; ++r) HID[crow(r, hi) * 264 + 32 * w + r32] = (bf16_t)(pkbf(gelu_tanh(acc[r]), 0.f) & 0xffffu);
	v_mfma_f32_32x32x16_bf16 v[2:17], v[152:155], v[184:187], v[2:17]
	s_waitcnt vmcnt(2)
	v_mfma_f32_32x32x16_bf16 v[2:17], v[156:159], v[188:191], v[2:17]
	s_waitcnt vmcnt(1)
	v_mfma_f32_32x32x16_bf16 v[2:17], v[160:163], v[192:195], v[2:17]
	s_waitcnt vmcnt(0)
	v_mfma_f32_32x32x16_bf16 v[2:17], v[164:167], v[196:199], v[2:17]
	s_nop 10
	v_mul_f32_e32 v18, 0x3d372713, v2
	v_mul_f32_e32 v18, v2, v18
	v_fma_f32 v18, v2, v18, v2
	v_mul_f32_e32 v18, 0x3f4c422a, v18
	v_add_f32_e32 v18, v18, v18
	v_mul_f32_e32 v18, 0x3fb8aa3b, v18
	v_exp_f32_e32 v19, v18
	v_mul_f32_e32 v2, 0.5, v2
	v_lshlrev_b32_e32 v18, 2, v40
	v_add_f32_e32 v19, 1.0, v19
	v_div_scale_f32 v20, s[16:17], v19, v19, 2.0
	v_rcp_f32_e32 v21, v20
	s_lshl_b32 s16, s10, 1
	s_add_i32 s16, s16, 0
	v_lshl_add_u32 v22, v41, 1, s16
	v_fma_f32 v23, -v20, v21, 1.0
	v_fmac_f32_e32 v21, v23, v21
	v_div_scale_f32 v23, vcc, 2.0, v19, 2.0
	v_mul_f32_e32 v24, v23, v21
	v_fma_f32 v25, -v20, v24, v23
	v_fmac_f32_e32 v24, v25, v21
	v_fma_f32 v20, -v20, v24, v23
	v_div_fmas_f32 v20, v20, v21, v24
	v_div_fixup_f32 v19, v20, v19, 2.0
	v_mul_f32_e32 v20, 0x3d372713, v3
	v_mul_f32_e32 v20, v3, v20
	v_fma_f32 v20, v3, v20, v3
	v_mul_f32_e32 v20, 0x3f4c422a, v20
	v_add_f32_e32 v20, v20, v20
	v_mul_f32_e32 v20, 0x3fb8aa3b, v20
	v_exp_f32_e32 v20, v20
	v_sub_f32_e32 v19, 1.0, v19
	v_add_f32_e32 v19, 1.0, v19
	v_mul_f32_e32 v2, v2, v19
	v_add_f32_e32 v19, 1.0, v20
	v_div_scale_f32 v20, s[16:17], v19, v19, 2.0
	v_rcp_f32_e32 v21, v20
	s_movk_i32 s16, 0x840
	v_cvt_pk_bf16_f32 v2, v2, s0
	v_mad_u32_u24 v23, v40, s16, v22
	ds_write_b16 v23, v2
	v_fma_f32 v2, -v20, v21, 1.0
	v_fmac_f32_e32 v21, v2, v21
	v_div_scale_f32 v2, vcc, 2.0, v19, 2.0
	v_mul_f32_e32 v23, v2, v21
	v_fma_f32 v24, -v20, v23, v2
	v_fmac_f32_e32 v23, v24, v21
	v_fma_f32 v2, -v20, v23, v2
	v_div_fmas_f32 v2, v2, v21, v23
	v_div_fixup_f32 v2, v2, v19, 2.0
	v_mul_f32_e32 v19, 0x3d372713, v4
	v_mul_f32_e32 v19, v4, v19
	v_fma_f32 v19, v4, v19, v4
	v_mul_f32_e32 v19, 0x3f4c422a, v19
	v_add_f32_e32 v19, v19, v19
	v_mul_f32_e32 v19, 0x3fb8aa3b, v19
	v_exp_f32_e32 v19, v19
	v_sub_f32_e32 v2, 1.0, v2
	v_mul_f32_e32 v3, 0.5, v3
	v_add_f32_e32 v2, 1.0, v2
	v_mul_f32_e32 v2, v3, v2
	v_add_f32_e32 v3, 1.0, v19
	v_div_scale_f32 v19, s[16:17], v3, v3, 2.0
	v_rcp_f32_e32 v20, v19
	v_or_b32_e32 v21, 1, v18
	s_movk_i32 s16, 0x210
	v_cvt_pk_bf16_f32 v2, v2, s0
	v_mad_u32_u24 v22, v21, s16, v22
	ds_write_b16 v22, v2
	v_fma_f32 v2, -v19, v20, 1.0
	v_fmac_f32_e32 v20, v2, v20
	v_div_scale_f32 v2, vcc, 2.0, v3, 2.0
	v_mul_f32_e32 v23, v2, v20
	v_fma_f32 v24, -v19, v23, v2
	v_fmac_f32_e32 v23, v24, v20
	v_fma_f32 v2, -v19, v23, v2
	v_div_fmas_f32 v2, v2, v20, v23
	v_div_fixup_f32 v2, v2, v3, 2.0
	v_mul_f32_e32 v3, 0x3d372713, v5
	v_mul_f32_e32 v3, v5, v3
	v_fma_f32 v3, v5, v3, v5
	v_mul_f32_e32 v3, 0x3f4c422a, v3
	v_add_f32_e32 v3, v3, v3
	v_mul_f32_e32 v3, 0x3fb8aa3b, v3
	v_exp_f32_e32 v3, v3
	v_sub_f32_e32 v2, 1.0, v2
	v_mul_f32_e32 v4, 0.5, v4
	v_add_f32_e32 v2, 1.0, v2
	v_add_f32_e32 v3, 1.0, v3
	v_div_scale_f32 v19, s[16:17], v3, v3, 2.0
	v_rcp_f32_e32 v20, v19
	v_mul_f32_e32 v2, v4, v2
	v_cvt_pk_bf16_f32 v2, v2, s0
	ds_write_b16 v22, v2 offset:528
	v_fma_f32 v2, -v19, v20, 1.0
	v_fmac_f32_e32 v20, v2, v20
	v_div_scale_f32 v2, vcc, 2.0, v3, 2.0
	v_mul_f32_e32 v4, v2, v20
	v_fma_f32 v23, -v19, v4, v2
	v_fmac_f32_e32 v4, v23, v20
	v_fma_f32 v2, -v19, v4, v2
	v_div_fmas_f32 v2, v2, v20, v4
	v_div_fixup_f32 v2, v2, v3, 2.0
	v_mul_f32_e32 v3, 0x3d372713, v6
	v_mul_f32_e32 v3, v6, v3
	v_fma_f32 v3, v6, v3, v6
	v_mul_f32_e32 v3, 0x3f4c422a, v3
	v_add_f32_e32 v3, v3, v3
	v_mul_f32_e32 v3, 0x3fb8aa3b, v3
	v_exp_f32_e32 v3, v3
	v_mul_f32_e32 v4, 0.5, v5
	v_sub_f32_e32 v2, 1.0, v2
	v_add_f32_e32 v2, 1.0, v2
	v_add_f32_e32 v3, 1.0, v3
	v_div_scale_f32 v5, s[16:17], v3, v3, 2.0
	v_rcp_f32_e32 v19, v5
	v_mul_f32_e32 v2, v4, v2
	v_cvt_pk_bf16_f32 v2, v2, s0
	ds_write_b16 v22, v2 offset:1056
	v_fma_f32 v2, -v5, v19, 1.0
	v_fmac_f32_e32 v19, v2, v19
	v_div_scale_f32 v2, vcc, 2.0, v3, 2.0
	v_mul_f32_e32 v4, v2, v19
	v_fma_f32 v20, -v5, v4, v2
	v_fmac_f32_e32 v4, v20, v19
	v_fma_f32 v2, -v5, v4, v2
	v_div_fmas_f32 v2, v2, v19, v4
	v_div_fixup_f32 v2, v2, v3, 2.0
	v_mul_f32_e32 v3, 0x3d372713, v7
	v_mul_f32_e32 v3, v7, v3
	v_fma_f32 v3, v7, v3, v7
	v_mul_f32_e32 v3, 0x3f4c422a, v3
	v_add_f32_e32 v3, v3, v3
	v_mul_f32_e32 v3, 0x3fb8aa3b, v3
	v_exp_f32_e32 v3, v3
	v_sub_f32_e32 v2, 1.0, v2
	v_mul_f32_e32 v4, 0.5, v6
	v_add_f32_e32 v2, 1.0, v2
	v_add_f32_e32 v3, 1.0, v3
	v_div_scale_f32 v5, s[16:17], v3, v3, 2.0
	v_rcp_f32_e32 v6, v5
	v_mul_f32_e32 v2, v4, v2
	v_cvt_pk_bf16_f32 v2, v2, s0
	ds_write_b16 v22, v2 offset:3696
	v_fma_f32 v2, -v5, v6, 1.0
	v_fmac_f32_e32 v6, v2, v6
	v_div_scale_f32 v2, vcc, 2.0, v3, 2.0
	v_mul_f32_e32 v4, v2, v6
	v_fma_f32 v19, -v5, v4, v2
	v_fmac_f32_e32 v4, v19, v6
	v_fma_f32 v2, -v5, v4, v2
	v_div_fmas_f32 v2, v2, v6, v4
	v_div_fixup_f32 v2, v2, v3, 2.0
	v_mul_f32_e32 v3, 0x3d372713, v8
	v_mul_f32_e32 v3, v8, v3
	v_fma_f32 v3, v8, v3, v8
	v_mul_f32_e32 v3, 0x3f4c422a, v3
	v_add_f32_e32 v3, v3, v3
	v_mul_f32_e32 v3, 0x3fb8aa3b, v3
	v_exp_f32_e32 v3, v3
	v_sub_f32_e32 v2, 1.0, v2
	v_mul_f32_e32 v4, 0.5, v7
	v_add_f32_e32 v2, 1.0, v2
	v_add_f32_e32 v3, 1.0, v3
	v_div_scale_f32 v5, s[16:17], v3, v3, 2.0
	v_rcp_f32_e32 v6, v5
	v_mul_f32_e32 v2, v4, v2
	v_cvt_pk_bf16_f32 v2, v2, s0
	ds_write_b16 v22, v2 offset:4224
	v_fma_f32 v2, -v5, v6, 1.0
	v_fmac_f32_e32 v6, v2, v6
	v_div_scale_f32 v2, vcc, 2.0, v3, 2.0
	v_mul_f32_e32 v4, v2, v6
	v_fma_f32 v7, -v5, v4, v2
	v_fmac_f32_e32 v4, v7, v6
	v_fma_f32 v2, -v5, v4, v2
	v_div_fmas_f32 v2, v2, v6, v4
	v_div_fixup_f32 v2, v2, v3, 2.0
; __device__ __forceinline__ int crow(int r, int hi) { return (r & 3) + 8 * (r >> 2) + 4 * hi; }
; __device__ __forceinline__ float gelu_tanh(float x) {
;     const float u = 0.7978845608028654f * (x + 0.044715f * x * x * x);
;     const float t = 1.f - 2.f / (1.f + __expf(2.f * u));
;     return 0.5f * x * (1.f + t);
; }
; __device__ __forceinline__ void compress_unit(LAS unsigned char* lds, int u, const bf16_t* QKV, const float* pe_k, const float* pe_v,
;                                               const bf16_t* CW1  , const bf16_t* CW2  , bf16_t* KCMP, bf16_t* VCMP) {
;     ...
;     for (int r = 0; r < 16; ++r) HID[crow(r, hi) * 264 + 32 * w + r32] = (bf16_t)(pkbf(gelu_tanh(acc[r]), 0.f) & 0xffffu);
;     __syncthreads();
	v_mul_f32_e32 v3, 0x3d372713, v9
	v_mul_f32_e32 v3, v9, v3
	v_fma_f32 v3, v9, v3, v9
	v_mul_f32_e32 v3, 0x3f4c422a, v3
	v_add_f32_e32 v3, v3, v3
	v_mul_f32_e32 v3, 0x3fb8aa3b, v3
	v_exp_f32_e32 v3, v3
	v_sub_f32_e32 v2, 1.0, v2
	v_mul_f32_e32 v4, 0.5, v8
	v_add_f32_e32 v2, 1.0, v2
	v_add_f32_e32 v3, 1.0, v3
	v_div_scale_f32 v5, s[16:17], v3, v3, 2.0
	v_rcp_f32_e32 v6, v5
	v_mul_f32_e32 v2, v4, v2
	v_cvt_pk_bf16_f32 v2, v2, s0
	ds_write_b16 v22, v2 offset:4752
	v_fma_f32 v2, -v5, v6, 1.0
	v_fmac_f32_e32 v6, v2, v6
	v_div_scale_f32 v2, vcc, 2.0, v3, 2.0
	v_mul_f32_e32 v4, v2, v6
	v_fma_f32 v7, -v5, v4, v2
	v_fmac_f32_e32 v4, v7, v6
	v_fma_f32 v2, -v5, v4, v2
	v_div_fmas_f32 v2, v2, v6, v4
	v_div_fixup_f32 v2, v2, v3, 2.0
	v_mul_f32_e32 v3, 0x3d372713, v10
	v_mul_f32_e32 v3, v10, v3
	v_fma_f32 v3, v10, v3, v10
	v_mul_f32_e32 v3, 0x3f4c422a, v3
	v_add_f32_e32 v3, v3, v3
	v_mul_f32_e32 v3, 0x3fb8aa3b, v3
	v_exp_f32_e32 v3, v3
	v_sub_f32_e32 v2, 1.0, v2
	v_mul_f32_e32 v4, 0.5, v9
	v_add_f32_e32 v2, 1.0, v2
	v_add_f32_e32 v3, 1.0, v3
	v_div_scale_f32 v5, s[16:17], v3, v3, 2.0
	v_rcp_f32_e32 v6, v5
	v_mul_f32_e32 v2, v4, v2
	v_cvt_pk_bf16_f32 v2, v2, s0
	ds_write_b16 v22, v2 offset:5280
	v_fma_f32 v2, -v5, v6, 1.0
	v_fmac_f32_e32 v6, v2, v6
	v_div_scale_f32 v2, vcc, 2.0, v3, 2.0
	v_mul_f32_e32 v4, v2, v6
	v_fma_f32 v7, -v5, v4, v2
	v_fmac_f32_e32 v4, v7, v6
	v_fma_f32 v2, -v5, v4, v2
	v_div_fmas_f32 v2, v2, v6, v4
	v_div_fixup_f32 v2, v2, v3, 2.0
	v_mul_f32_e32 v3, 0x3d372713, v11
	v_mul_f32_e32 v3, v11, v3
	v_fma_f32 v3, v11, v3, v11
	v_mul_f32_e32 v3, 0x3f4c422a, v3
	v_add_f32_e32 v3, v3, v3
	v_mul_f32_e32 v3, 0x3fb8aa3b, v3
	v_exp_f32_e32 v3, v3
	v_sub_f32_e32 v2, 1.0, v2
	v_mul_f32_e32 v4, 0.5, v10
	v_add_f32_e32 v2, 1.0, v2
	v_add_f32_e32 v3, 1.0, v3
	v_div_scale_f32 v5, s[16:17], v3, v3, 2.0
	v_rcp_f32_e32 v6, v5
	v_mul_f32_e32 v2, v4, v2
	v_cvt_pk_bf16_f32 v2, v2, s0
	ds_write_b16 v22, v2 offset:7920
	v_fma_f32 v2, -v5, v6, 1.0
	v_fmac_f32_e32 v6, v2, v6
	v_div_scale_f32 v2, vcc, 2.0, v3, 2.0
	v_mul_f32_e32 v4, v2, v6
	v_fma_f32 v7, -v5, v4, v2
	v_fmac_f32_e32 v4, v7, v6
	v_fma_f32 v2, -v5, v4, v2
	v_div_fmas_f32 v2, v2, v6, v4
	v_div_fixup_f32 v2, v2, v3, 2.0
	v_mul_f32_e32 v3, 0x3d372713, v12
	v_mul_f32_e32 v3, v12, v3
	v_fma_f32 v3, v12, v3, v12
	v_mul_f32_e32 v3, 0x3f4c422a, v3
	v_add_f32_e32 v3, v3, v3
	v_mul_f32_e32 v3, 0x3fb8aa3b, v3
	v_exp_f32_e32 v3, v3
	v_sub_f32_e32 v2, 1.0, v2
	v_mul_f32_e32 v4, 0.5, v11
	v_add_f32_e32 v2, 1.0, v2
	v_add_f32_e32 v3, 1.0, v3
	v_div_scale_f32 v5, s[16:17], v3, v3, 2.0
	v_rcp_f32_e32 v6, v5
	v_mul_f32_e32 v2, v4, v2
	v_cvt_pk_bf16_f32 v2, v2, s0
	ds_write_b16 v22, v2 offset:8448
	v_fma_f32 v2, -v5, v6, 1.0
	v_fmac_f32_e32 v6, v2, v6
	v_div_scale_f32 v2, vcc, 2.0, v3, 2.0
	v_mul_f32_e32 v4, v2, v6
	v_fma_f32 v7, -v5, v4, v2
	v_fmac_f32_e32 v4, v7, v6
	v_fma_f32 v2, -v5, v4, v2
	v_div_fmas_f32 v2, v2, v6, v4
	v_div_fixup_f32 v2, v2, v3, 2.0
	v_mul_f32_e32 v3, 0x3d372713, v13
	v_mul_f32_e32 v3, v13, v3
	v_fma_f32 v3, v13, v3, v13
	v_mul_f32_e32 v3, 0x3f4c422a, v3
	v_add_f32_e32 v3, v3, v3
	v_mul_f32_e32 v3, 0x3fb8aa3b, v3
	v_exp_f32_e32 v3, v3
	v_sub_f32_e32 v2, 1.0, v2
	v_mul_f32_e32 v4, 0.5, v12
	v_add_f32_e32 v2, 1.0, v2
	v_add_f32_e32 v3, 1.0, v3
	v_div_scale_f32 v5, s[16:17], v3, v3, 2.0
	v_rcp_f32_e32 v6, v5
	v_mul_f32_e32 v2, v4, v2
	v_cvt_pk_bf16_f32 v2, v2, s0
	ds_write_b16 v22, v2 offset:8976
	v_fma_f32 v2, -v5, v6, 1.0
	v_fmac_f32_e32 v6, v2, v6
	v_div_scale_f32 v2, vcc, 2.0, v3, 2.0
	v_mul_f32_e32 v4, v2, v6
	v_fma_f32 v7, -v5, v4, v2
	v_fmac_f32_e32 v4, v7, v6
	v_fma_f32 v2, -v5, v4, v2
	v_div_fmas_f32 v2, v2, v6, v4
	v_div_fixup_f32 v2, v2, v3, 2.0
	v_mul_f32_e32 v3, 0x3d372713, v14
	v_mul_f32_e32 v3, v14, v3
	v_fma_f32 v3, v14, v3, v14
	v_mul_f32_e32 v3, 0x3f4c422a, v3
	v_add_f32_e32 v3, v3, v3
	v_mul_f32_e32 v3, 0x3fb8aa3b, v3
	v_exp_f32_e32 v3, v3
	v_sub_f32_e32 v2, 1.0, v2
	v_mul_f32_e32 v4, 0.5, v13
	v_add_f32_e32 v2, 1.0, v2
	v_add_f32_e32 v3, 1.0, v3
	v_div_scale_f32 v5, s[16:17], v3, v3, 2.0
	v_rcp_f32_e32 v6, v5
	v_mul_f32_e32 v2, v4, v2
	v_cvt_pk_bf16_f32 v2, v2, s0
	ds_write_b16 v22, v2 offset:9504
	v_fma_f32 v2, -v5, v6, 1.0
	v_fmac_f32_e32 v6, v2, v6
	v_div_scale_f32 v2, vcc, 2.0, v3, 2.0
	v_mul_f32_e32 v4, v2, v6
	v_fma_f32 v7, -v5, v4, v2
	v_fmac_f32_e32 v4, v7, v6
	v_fma_f32 v2, -v5, v4, v2
	v_div_fmas_f32 v2, v2, v6, v4
	v_div_fixup_f32 v2, v2, v3, 2.0
	v_mul_f32_e32 v3, 0x3d372713, v15
	v_mul_f32_e32 v3, v15, v3
	v_fma_f32 v3, v15, v3, v15
	v_mul_f32_e32 v3, 0x3f4c422a, v3
	v_add_f32_e32 v3, v3, v3
	v_mul_f32_e32 v3, 0x3fb8aa3b, v3
	v_exp_f32_e32 v3, v3
	v_sub_f32_e32 v2, 1.0, v2
	v_mul_f32_e32 v4, 0.5, v14
	v_add_f32_e32 v2, 1.0, v2
	v_add_f32_e32 v3, 1.0, v3
	v_div_scale_f32 v5, s[16:17], v3, v3, 2.0
	v_rcp_f32_e32 v6, v5
	v_mul_f32_e32 v2, v4, v2
	v_cvt_pk_bf16_f32 v2, v2, s0
	ds_write_b16 v22, v2 offset:12144
	v_fma_f32 v2, -v5, v6, 1.0
	v_fmac_f32_e32 v6, v2, v6
	v_div_scale_f32 v2, vcc, 2.0, v3, 2.0
	v_mul_f32_e32 v4, v2, v6
	v_fma_f32 v7, -v5, v4, v2
	v_fmac_f32_e32 v4, v7, v6
	v_fma_f32 v2, -v5, v4, v2
	v_div_fmas_f32 v2, v2, v6, v4
	v_div_fixup_f32 v2, v2, v3, 2.0
	v_mul_f32_e32 v3, 0x3d372713, v16
	v_mul_f32_e32 v3, v16, v3
	v_fma_f32 v3, v16, v3, v16
	v_mul_f32_e32 v3, 0x3f4c422a, v3
	v_add_f32_e32 v3, v3, v3
	v_mul_f32_e32 v3, 0x3fb8aa3b, v3
	v_exp_f32_e32 v3, v3
	v_sub_f32_e32 v2, 1.0, v2
	v_mul_f32_e32 v4, 0.5, v15
	v_add_f32_e32 v2, 1.0, v2
	v_add_f32_e32 v3, 1.0, v3
	v_div_scale_f32 v5, s[16:17], v3, v3, 2.0
	v_rcp_f32_e32 v6, v5
	v_mul_f32_e32 v2, v4, v2
	v_cvt_pk_bf16_f32 v2, v2, s0
	ds_write_b16 v22, v2 offset:12672
	v_fma_f32 v2, -v5, v6, 1.0
	v_fmac_f32_e32 v6, v2, v6
	v_div_scale_f32 v2, vcc, 2.0, v3, 2.0
	v_mul_f32_e32 v4, v2, v6
	v_fma_f32 v7, -v5, v4, v2
	v_fmac_f32_e32 v4, v7, v6
	v_fma_f32 v2, -v5, v4, v2
	v_div_fmas_f32 v2, v2, v6, v4
	v_div_fixup_f32 v2, v2, v3, 2.0
	v_mul_f32_e32 v3, 0x3d372713, v17
	v_mul_f32_e32 v3, v17, v3
	v_fma_f32 v3, v17, v3, v17
	v_mul_f32_e32 v3, 0x3f4c422a, v3
	v_add_f32_e32 v3, v3, v3
	v_mul_f32_e32 v3, 0x3fb8aa3b, v3
	v_exp_f32_e32 v3, v3
	v_sub_f32_e32 v2, 1.0, v2
	v_mul_f32_e32 v4, 0.5, v16
	v_add_f32_e32 v2, 1.0, v2
	v_add_f32_e32 v3, 1.0, v3
	v_div_scale_f32 v5, s[16:17], v3, v3, 2.0
	v_rcp_f32_e32 v6, v5
	v_mul_f32_e32 v2, v4, v2
	v_cvt_pk_bf16_f32 v2, v2, s0
	ds_write_b16 v22, v2 offset:13200
	v_fma_f32 v2, -v5, v6, 1.0
	v_fmac_f32_e32 v6, v2, v6
	v_div_scale_f32 v2, vcc, 2.0, v3, 2.0
	v_mul_f32_e32 v4, v2, v6
	v_fma_f32 v7, -v5, v4, v2
	v_fmac_f32_e32 v4, v7, v6
	v_fma_f32 v2, -v5, v4, v2
	v_div_fmas_f32 v2, v2, v6, v4
	v_div_fixup_f32 v2, v2, v3, 2.0
	v_sub_f32_e32 v2, 1.0, v2
	v_mul_f32_e32 v3, 0.5, v17
	v_add_f32_e32 v2, 1.0, v2
	v_mul_f32_e32 v2, v3, v2
	v_cvt_pk_bf16_f32 v2, v2, s0
	s_cmp_lt_i32 s29, 2
	ds_write_b16 v22, v2 offset:13728
	s_waitcnt lgkmcnt(0)
	s_barrier
; #define LAS __attribute__((address_space(3)))
; __device__ __forceinline__ int crow(int r, int hi) { return (r & 3) + 8 * (r >> 2) + 4 * hi; }
; __device__ __forceinline__ v16f mfma32(v8s a, v8s b, v16f c) { return __builtin_amdgcn_mfma_f32_32x32x16_bf16(a, b, c, 0, 0, 0); }
; __device__ __forceinline__ void compress_unit(LAS unsigned char* lds, int u, const bf16_t* QKV, const float* pe_k, const float* pe_v,
;                                               const bf16_t* CW1  , const bf16_t* CW2  , bf16_t* KCMP, bf16_t* VCMP) {
;     ...
;     if (w < 2) {
;         v16f o;
; #pragma unroll
;         for (int r = 0; r < 16; ++r) o[r] = 0.f;
;         const bf16_t* B2 = W2 + (size_t)(32 * w + r32) * 256 + hi * 8;
; #pragma unroll
;         for (int st = 0; st < 16; ++st) {
;             const v8s af = *(const LAS v8s*)(HID + r32 * 264 + st * 16 + hi * 8);
;             const v8s bfr = *(const v8s*)(B2 + st * 16);
;             o = mfma32(af, bfr, o);
;         }
; #pragma unroll
;         for (int r = 0; r < 16; ++r) { const int nl = crow(r, hi); const bool valid = (ch * 32 + nl) < 255;
;             OUT[(size_t)nl * 64 + 32 * w + r32] = valid ? (bf16_t)(pkbf(o[r], 0.f) & 0xffffu) : (bf16_t)0; }
;     }
	s_cbranch_scc0 .LBB0_410
	s_and_b32 s16, s28, 1
	s_lshl_b32 s11, s11, 9
	s_lshl_b32 s16, s16, 8
	s_or_b32 s11, s11, s16
	s_or_b32 s11, s11, s27
	s_lshl_b64 s[12:13], s[12:13], 15
	s_and_b64 s[14:15], s[14:15], exec
	s_cselect_b32 s16, s22, s24
	s_cselect_b32 s17, s21, s23
	s_add_u32 s14, s19, s12
	s_addc_u32 s15, s20, s13
	v_lshlrev_b64 v[2:3], 9, v[34:35]
	v_lshl_add_u64 v[2:3], s[14:15], 0, v[2:3]
	v_lshlrev_b32_e32 v30, 7, v18
	v_or_b32_e32 v20, 27, v18
	v_lshl_add_u64 v[18:19], v[2:3], 0, v[0:1]
	v_mul_u32_u24_e32 v2, 0x210, v41
	v_add3_u32 v0, 0, v2, v0
	global_load_dwordx4 v[2:5], v[18:19], off
	ds_read_b128 v[6:9], v0
	ds_read_b128 v[22:25], v0 offset:32
	global_load_dwordx4 v[26:29], v[18:19], off offset:32
	s_lshl_b32 s11, s11, 7
	s_add_u32 s12, s17, s11
	s_addc_u32 s13, s16, 0
	s_ashr_i32 s11, s10, 31
	s_lshl_b64 s[10:11], s[10:11], 1
	s_add_u32 s10, s12, s10
	s_addc_u32 s11, s13, s11
	s_waitcnt vmcnt(1) lgkmcnt(1)
	v_mfma_f32_32x32x16_bf16 v[2:17], v[6:9], v[2:5], 0
	s_waitcnt vmcnt(0) lgkmcnt(0)
	v_mfma_f32_32x32x16_bf16 v[2:17], v[22:25], v[26:29], v[2:17]
	global_load_dwordx4 v[26:29], v[18:19], off offset:64
	ds_read_b128 v[22:25], v0 offset:64
	s_waitcnt vmcnt(0) lgkmcnt(0)
	v_mfma_f32_32x32x16_bf16 v[2:17], v[22:25], v[26:29], v[2:17]
	global_load_dwordx4 v[26:29], v[18:19], off offset:96
	ds_read_b128 v[22:25], v0 offset:96
	s_waitcnt vmcnt(0) lgkmcnt(0)
	v_mfma_f32_32x32x16_bf16 v[2:17], v[22:25], v[26:29], v[2:17]
	global_load_dwordx4 v[26:29], v[18:19], off offset:128
	ds_read_b128 v[22:25], v0 offset:128
	s_waitcnt vmcnt(0) lgkmcnt(0)
	v_mfma_f32_32x32x16_bf16 v[2:17], v[22:25], v[26:29], v[2:17]
	global_load_dwordx4 v[26:29], v[18:19], off offset:160
	ds_read_b128 v[22:25], v0 offset:160
	s_waitcnt vmcnt(0) lgkmcnt(0)
	v_mfma_f32_32x32x16_bf16 v[2:17], v[22:25], v[26:29], v[2:17]
	global_load_dwordx4 v[26:29], v[18:19], off offset:192
	ds_read_b128 v[22:25], v0 offset:192
	s_waitcnt vmcnt(0) lgkmcnt(0)
	v_mfma_f32_32x32x16_bf16 v[2:17], v[22:25], v[26:29], v[2:17]
	global_load_dwordx4 v[26:29], v[18:19], off offset:224
	ds_read_b128 v[22:25], v0 offset:224
	s_waitcnt vmcnt(0) lgkmcnt(0)
	v_mfma_f32_32x32x16_bf16 v[2:17], v[22:25], v[26:29], v[2:17]
	global_load_dwordx4 v[26:29], v[18:19], off offset:256
	ds_read_b128 v[22:25], v0 offset:256
	s_waitcnt vmcnt(0) lgkmcnt(0)
	v_mfma_f32_32x32x16_bf16 v[2:17], v[22:25], v[26:29], v[2:17]
	global_load_dwordx4 v[26:29], v[18:19], off offset:288
	ds_read_b128 v[22:25], v0 offset:288
	s_waitcnt vmcnt(0) lgkmcnt(0)
	v_mfma_f32_32x32x16_bf16 v[2:17], v[22:25], v[26:29], v[2:17]
	global_load_dwordx4 v[26:29], v[18:19], off offset:320
	ds_read_b128 v[22:25], v0 offset:320
	s_waitcnt vmcnt(0) lgkmcnt(0)
	v_mfma_f32_32x32x16_bf16 v[2:17], v[22:25], v[26:29], v[2:17]
	global_load_dwordx4 v[26:29], v[18:19], off offset:352
	ds_read_b128 v[22:25], v0 offset:352
	s_waitcnt vmcnt(0) lgkmcnt(0)
	v_mfma_f32_32x32x16_bf16 v[2:17], v[22:25], v[26:29], v[2:17]
	global_load_dwordx4 v[26:29], v[18:19], off offset:384
	ds_read_b128 v[22:25], v0 offset:384
	s_waitcnt vmcnt(0) lgkmcnt(0)
	v_mfma_f32_32x32x16_bf16 v[2:17], v[22:25], v[26:29], v[2:17]
	global_load_dwordx4 v[26:29], v[18:19], off offset:416
	ds_read_b128 v[22:25], v0 offset:416
	s_waitcnt vmcnt(0) lgkmcnt(0)
	v_mfma_f32_32x32x16_bf16 v[2:17], v[22:25], v[26:29], v[2:17]
	global_load_dwordx4 v[26:29], v[18:19], off offset:448
	ds_read_b128 v[22:25], v0 offset:448
	s_waitcnt vmcnt(0) lgkmcnt(0)
	v_mfma_f32_32x32x16_bf16 v[2:17], v[22:25], v[26:29], v[2:17]
	global_load_dwordx4 v[26:29], v[18:19], off offset:480
	ds_read_b128 v[22:25], v0 offset:480
	v_lshlrev_b32_e32 v0, 1, v41
	v_lshl_add_u64 v[18:19], s[10:11], 0, v[0:1]
	v_lshlrev_b32_e32 v0, 9, v40
	s_movk_i32 s10, 0xff
	s_waitcnt vmcnt(0) lgkmcnt(0)
	v_mfma_f32_32x32x16_bf16 v[2:17], v[22:25], v[26:29], v[2:17]
	v_lshl_add_u64 v[22:23], v[18:19], 0, v[0:1]
	v_lshlrev_b32_e32 v0, 7, v21
	s_nop 9
	v_cvt_pk_bf16_f32 v2, v2, s0
	global_store_short v[22:23], v2, off
	v_cvt_pk_bf16_f32 v22, v3, s0
	v_lshl_add_u64 v[2:3], v[18:19], 0, v[0:1]
	v_or_b32_e32 v0, 0x100, v30
	global_store_short v[2:3], v22, off
	v_cvt_pk_bf16_f32 v4, v4, s0
	v_lshl_add_u64 v[2:3], v[18:19], 0, v[0:1]
	v_or_b32_e32 v0, 0x180, v30
	global_store_short v[2:3], v4, off
	v_cvt_pk_bf16_f32 v4, v5, s0
	v_lshl_add_u64 v[2:3], v[18:19], 0, v[0:1]
	v_or_b32_e32 v0, 0x400, v30
	global_store_short v[2:3], v4, off
	v_cvt_pk_bf16_f32 v4, v6, s0
	v_lshl_add_u64 v[2:3], v[18:19], 0, v[0:1]
	v_or_b32_e32 v0, 0x480, v30
	global_store_short v[2:3], v4, off
	v_cvt_pk_bf16_f32 v4, v7, s0
	v_lshl_add_u64 v[2:3], v[18:19], 0, v[0:1]
	v_or_b32_e32 v0, 0x500, v30
	global_store_short v[2:3], v4, off
	v_cvt_pk_bf16_f32 v4, v8, s0
	v_lshl_add_u64 v[2:3], v[18:19], 0, v[0:1]
	v_or_b32_e32 v0, 0x580, v30
	global_store_short v[2:3], v4, off
	v_cvt_pk_bf16_f32 v4, v9, s0
	v_lshl_add_u64 v[2:3], v[18:19], 0, v[0:1]
	v_or_b32_e32 v0, 0x800, v30
	global_store_short v[2:3], v4, off
	v_cvt_pk_bf16_f32 v4, v10, s0
	v_lshl_add_u64 v[2:3], v[18:19], 0, v[0:1]
	v_or_b32_e32 v0, 0x880, v30
	global_store_short v[2:3], v4, off
	v_cvt_pk_bf16_f32 v4, v11, s0
	v_lshl_add_u64 v[2:3], v[18:19], 0, v[0:1]
	v_or_b32_e32 v0, 0x900, v30
	global_store_short v[2:3], v4, off
	v_cvt_pk_bf16_f32 v4, v12, s0
	v_lshl_add_u64 v[2:3], v[18:19], 0, v[0:1]
	v_or_b32_e32 v0, 0x980, v30
	global_store_short v[2:3], v4, off
	v_cvt_pk_bf16_f32 v4, v13, s0
	v_lshl_add_u64 v[2:3], v[18:19], 0, v[0:1]
	v_or_b32_e32 v0, 0xc00, v30
	global_store_short v[2:3], v4, off
	v_cvt_pk_bf16_f32 v4, v14, s0
	v_lshl_add_u64 v[2:3], v[18:19], 0, v[0:1]
	v_or_b32_e32 v0, 0xc80, v30
	global_store_short v[2:3], v4, off
	v_cvt_pk_bf16_f32 v4, v15, s0
	v_lshl_add_u64 v[2:3], v[18:19], 0, v[0:1]
	v_or_b32_e32 v0, 0xd00, v30
	global_store_short v[2:3], v4, off
	v_cvt_pk_bf16_f32 v4, v16, s0
	v_lshl_add_u64 v[2:3], v[18:19], 0, v[0:1]
	v_or_b32_e32 v0, s27, v20
	global_store_short v[2:3], v4, off
	v_cvt_pk_bf16_f32 v2, v17, s0
	v_cmp_ne_u32_e32 vcc, s10, v0
	v_lshlrev_b32_e32 v0, 7, v20
	s_nop 0
	v_cndmask_b32_e32 v4, 0, v2, vcc
	v_lshl_add_u64 v[2:3], v[18:19], 0, v[0:1]
	global_store_short v[2:3], v4, off
	s_branch .LBB0_410
